# comb1 + conv row-load fast path + gMLP LN/out-norm gain tables staged in LDS (fewer vector-memory instructions)
# speedup vs baseline: 1.0011x; 1.0001x over previous
; __global__ void __launch_bounds__(NTHR, 2) fwd_megakernel(Args args) {
;     ...
;             for (int hf = 0; hf < 2; ++hf) {
;                 f32x2 ov[16];
; #pragma unroll
;                 for (int r = 0; r < 16; ++r) ov[r] = cb;
;                 ConvJ<0>::run(ov, wk, AB + 2 * tid, t0 + 16 * hf, tb);
.LBB0_565:
	s_lshl_b32 s2, s63, 4
	s_or_b32 s20, s2, s62
	s_sub_i32 s2, s20, 30
	s_cmp_lt_i32 s2, s11
	s_cbranch_scc1 .Lconv_rows_slow
	s_ashr_i32 s3, s2, 31
	s_lshl_b64 s[2:3], s[2:3], 11
	v_lshl_add_u64 v[144:145], v[24:25], 0, s[2:3]
	s_mov_b64 s[18:19], 0x1000
	global_load_dword v138, v[144:145], off
	global_load_dword v228, v[144:145], off offset:2048
	v_lshl_add_u64 v[144:145], v[144:145], 0, s[18:19]
	global_load_dword v229, v[144:145], off
	global_load_dword v230, v[144:145], off offset:2048
	v_lshl_add_u64 v[144:145], v[144:145], 0, s[18:19]
	global_load_dword v231, v[144:145], off
	global_load_dword v232, v[144:145], off offset:2048
	v_lshl_add_u64 v[144:145], v[144:145], 0, s[18:19]
	global_load_dword v233, v[144:145], off
	global_load_dword v234, v[144:145], off offset:2048
	v_lshl_add_u64 v[144:145], v[144:145], 0, s[18:19]
	global_load_dword v212, v[144:145], off
	global_load_dword v207, v[144:145], off offset:2048
	v_lshl_add_u64 v[144:145], v[144:145], 0, s[18:19]
	global_load_dword v201, v[144:145], off
	global_load_dword v195, v[144:145], off offset:2048
	v_lshl_add_u64 v[144:145], v[144:145], 0, s[18:19]
	global_load_dword v189, v[144:145], off
	global_load_dword v183, v[144:145], off offset:2048
	v_lshl_add_u64 v[144:145], v[144:145], 0, s[18:19]
	global_load_dword v139, v[144:145], off
	global_load_dword v141, v[144:145], off offset:2048
	v_lshl_add_u64 v[144:145], v[144:145], 0, s[18:19]
	global_load_dword v143, v[144:145], off
	global_load_dword v147, v[144:145], off offset:2048
	v_lshl_add_u64 v[144:145], v[144:145], 0, s[18:19]
	global_load_dword v149, v[144:145], off
	global_load_dword v151, v[144:145], off offset:2048
	v_lshl_add_u64 v[144:145], v[144:145], 0, s[18:19]
	global_load_dword v153, v[144:145], off
	global_load_dword v155, v[144:145], off offset:2048
	v_lshl_add_u64 v[144:145], v[144:145], 0, s[18:19]
	global_load_dword v157, v[144:145], off
	global_load_dword v159, v[144:145], off offset:2048
	v_lshl_add_u64 v[144:145], v[144:145], 0, s[18:19]
	global_load_dword v161, v[144:145], off
	global_load_dword v163, v[144:145], off offset:2048
	v_lshl_add_u64 v[144:145], v[144:145], 0, s[18:19]
	global_load_dword v165, v[144:145], off
	global_load_dword v167, v[144:145], off offset:2048
	v_lshl_add_u64 v[144:145], v[144:145], 0, s[18:19]
	global_load_dword v169, v[144:145], off
	global_load_dword v171, v[144:145], off offset:2048
	v_lshl_add_u64 v[144:145], v[144:145], 0, s[18:19]
	global_load_dword v173, v[144:145], off
	global_load_dword v175, v[144:145], off offset:2048
	v_lshl_add_u64 v[144:145], v[144:145], 0, s[18:19]
	global_load_dword v177, v[144:145], off
	global_load_dword v176, v[144:145], off offset:2048
	v_lshl_add_u64 v[144:145], v[144:145], 0, s[18:19]
	global_load_dword v181, v[144:145], off
	global_load_dword v180, v[144:145], off offset:2048
	v_lshl_add_u64 v[144:145], v[144:145], 0, s[18:19]
	global_load_dword v184, v[144:145], off
	global_load_dword v182, v[144:145], off offset:2048
	v_lshl_add_u64 v[144:145], v[144:145], 0, s[18:19]
	global_load_dword v188, v[144:145], off
	global_load_dword v185, v[144:145], off offset:2048
	v_lshl_add_u64 v[144:145], v[144:145], 0, s[18:19]
	global_load_dword v191, v[144:145], off
	global_load_dword v190, v[144:145], off offset:2048
	v_lshl_add_u64 v[144:145], v[144:145], 0, s[18:19]
	global_load_dword v196, v[144:145], off
	global_load_dword v194, v[144:145], off offset:2048
	v_lshl_add_u64 v[144:145], v[144:145], 0, s[18:19]
	global_load_dword v197, v[144:145], off
	global_load_dword v235, v[144:145], off offset:2048
	s_branch .LBB0_564
.Lconv_rows_slow:
	s_sub_i32 s2, s20, 30
	v_mov_b32_e32 v228, 0
	s_cmp_ge_i32 s2, s11
	v_mov_b32_e32 v138, 0
	s_cbranch_scc0 .LBB0_567
	s_ashr_i32 s3, s2, 31
	s_lshl_b64 s[2:3], s[2:3], 11
	v_lshl_add_u64 v[138:139], v[24:25], 0, s[2:3]
	global_load_dword v138, v[138:139], off

; #define LAS __attribute__((address_space(3)))
; __device__ __forceinline__ unsigned cvt_pk_bf16(float lo, float hi) { unsigned r; asm volatile("v_cvt_pk_bf16_f32 %0, %1, %2" : "=v"(r) : "v"(lo), "v"(hi)); return r; }
; #define KIN(i) (*(const float* const __attribute__((address_space(4)))*)(kp + kz + 8 * (i)))
; __global__ void __launch_bounds__(NTHR, 2) fwd_megakernel(Args args) {
;     ...
;             const int tc0 = (su >> 2) * 128, qi = su & 3, i0 = 32 * qi, J = qi < 2 ? 64 : 128;
;             constexpr int LDB = 136;
;             LAS bf16_t* Bt = (LAS bf16_t*)lds;
;             LAS f32x2* st = (LAS f32x2*)(lds + 2 * 128 * LDB * 2);
;             LAS float* red = (LAS float*)(lds + 2 * 128 * LDB * 2 + 1024);
;             if (tid < J) { const f32x4* p = (const f32x4*)(VSTAT + (size_t)(tc0 + tid) * 32); float s1 = 0.f, s2 = 0.f;
; #pragma unroll
;                 for (int j = 0; j < 8; ++j) { const f32x4 v = p[j]; s1 += v[0] + v[2]; s2 += v[1] + v[3]; }
;                 const float mean = s1 * (1.0f / CCH), var = fmaxf(s2 * (1.0f / CCH) - mean * mean, 0.f); st[tid] = (f32x2){mean, rsqrtf(var + LN_EPS)}; }
;             const int mb = wave & 1, nq = wave >> 1, fr = lane & 15, fq = lane >> 4;
;             const int trow = tc0 + i0 + 16 * mb + fr;
;             const float* lng = KIN(I_SGU_LN_G); const float* lnb = KIN(I_SGU_LN_B); const float* sgb = KIN(I_SGU_B);
;             const int c8 = tid & 15, jb = tid >> 4, nk = J / 32;
;             u32x4 pv[4]; f32x4 pg0, pg1, pb0, pb1; bf16x8 pw[4]; u32x2 pu0, pu1; float pbs;
;     ...
; #pragma unroll
;             for (int h = 0; h < 8; ++h)
; #pragma unroll
;                 for (int nb = 0; nb < 2; ++nb) { const int ch = h * 128 + 32 * nq + 16 * nb + 4 * fq; const f32x4 gg = *(const f32x4*)(KIN(I_OUT_NORM_SGU) + ch); const f32x4 y = yv[h][nb] * r2 * gg;
;                     u32x2 w; w.x = cvt_pk_bf16(y[0], y[1]); w.y = cvt_pk_bf16(y[2], y[3]); *(u32x2*)(Y + (size_t)trow * D + CCH + ch) = w; }
.LBB0_657:
	v_readlane_b32 s2, v254, 3
	s_add_i32 s11, 0, 0x11000
	s_bfe_u32 s4, s2, 0x10006
	s_lshr_b32 s5, s2, 7
	v_and_b32_e32 v2, 15, v221
	s_add_u32 s2, s0, s42
	v_mov_b32_e32 v121, 0
	v_lshl_or_b32 v155, s4, 4, v2
	s_addc_u32 s3, s1, s43
	v_and_b32_e32 v0, 48, v220
	v_mov_b32_e32 v1, v121
	s_lshl_b32 s4, s4, 8
	s_load_dwordx4 s[24:27], s[2:3], 0x58
	s_load_dwordx2 s[20:21], s[2:3], 0x70
	s_load_dwordx2 s[100:101], s[2:3], 0x80
	v_lshl_add_u64 v[0:1], s[14:15], 0, v[0:1]
	s_mov_b64 s[2:3], 0xbc00000
	s_add_i32 s4, s4, 0
	v_lshl_add_u64 v[128:129], v[0:1], 0, s[2:3]
	s_lshl_b32 s18, s5, 5
	v_mov_b32_e32 v0, 0x68
	s_add_i32 s4, s4, 0x11400
	s_lshl_b32 s5, s5, 6
	v_lshlrev_b32_e32 v120, 4, v2
	v_bitop3_b32 v7, s18, v0, v2 bitop3:0xc8
	s_add_i32 s23, s4, s5
	v_lshlrev_b32_e32 v0, 2, v2
	v_lshrrev_b32_e32 v3, 4, v220
	v_lshl_add_u64 v[122:123], s[36:37], 0, v[120:121]
	v_lshlrev_b32_e32 v120, 5, v2
	v_add_u32_e32 v175, s4, v0
	s_add_u32 s4, s88, s5
	s_waitcnt lgkmcnt(0)
	v_lshl_add_u64 v[124:125], s[24:25], 0, v[120:121]
	v_lshl_add_u64 v[126:127], s[26:27], 0, v[120:121]
	v_lshlrev_b32_e32 v120, 3, v3
	s_addc_u32 s5, s89, 0
	v_lshrrev_b32_e32 v163, 4, v221
	v_lshlrev_b32_e32 v4, 3, v2
	v_lshl_add_u64 v[130:131], s[4:5], 0, v[120:121]
	s_movk_i32 s4, 0x880
	v_or_b32_e32 v1, s18, v2
	v_add_u32_e32 v169, s23, v0
	v_lshl_or_b32 v0, v3, 2, s18
	v_mad_u32_u24 v2, v2, s4, 0
	v_xor_b32_e32 v3, v163, v4
	v_lshl_add_u32 v186, v3, 1, v2
	v_add_u32_e32 v3, 32, v163
	v_lshl_add_u32 v187, v3, 3, s11
	v_xor_b32_e32 v3, v3, v4
	v_lshl_add_u32 v188, v3, 1, v2
	v_or_b32_e32 v3, 64, v163
	v_lshl_add_u32 v189, v3, 3, s11
	v_bitop3_b32 v3, v163, v4, 64 bitop3:0x36
	s_movk_i32 s2, 0x110
	v_lshl_add_u32 v190, v3, 1, v2
	v_add_u32_e32 v3, 0x60, v163
	v_mul_lo_u32 v6, v1, s2
	s_movk_i32 s19, 0x68
	s_movk_i32 s22, 0x78
	v_lshl_add_u32 v191, v3, 3, s11
	v_xor_b32_e32 v3, v3, v4
	v_or_b32_e32 v5, 16, v1
	v_bitop3_b32 v8, v1, s22, 16 bitop3:0xc8
	v_lshl_add_u32 v192, v3, 1, v2
	v_add_u32_e32 v2, 0, v6
	v_bitop3_b32 v1, v120, v1, s19 bitop3:0x78
	v_add_u32_e32 v3, 0x1100, v2
	v_lshl_add_u32 v193, v1, 1, v2
	v_bitop3_b32 v1, v120, v5, s22 bitop3:0x78
	v_lshl_add_u32 v194, v1, 1, v3
	v_bitop3_b32 v1, v120, v7, 32 bitop3:0x36
	v_lshl_add_u32 v195, v1, 1, v2
	v_bitop3_b32 v1, v120, v8, 32 bitop3:0x36
	v_lshl_add_u32 v196, v1, 1, v3
	v_bitop3_b32 v1, v120, v7, 64 bitop3:0x36
	s_movk_i32 s4, 0x60
	v_lshl_add_u32 v197, v1, 1, v2
	v_bitop3_b32 v1, v120, v8, 64 bitop3:0x36
	v_lshl_add_u32 v198, v1, 1, v3
	v_bitop3_b32 v1, v120, v7, s4 bitop3:0x36
	v_lshl_add_u32 v199, v1, 1, v2
	v_bitop3_b32 v1, v120, v8, s4 bitop3:0x36
	v_lshlrev_b32_e32 v120, 1, v0
	v_lshl_add_u32 v137, v221, 3, s11
	v_cmp_gt_u32_e64 s[2:3], 16, v220
	v_lshl_add_u32 v181, v163, 3, s11
	v_lshl_add_u32 v200, v1, 1, v3
	v_lshl_add_u64 v[132:133], s[6:7], 0, v[120:121]
	s_lshl_b32 s23, s10, 5
	s_lshl_b32 s56, s34, 5
	s_mov_b32 s22, 0x3a800000
	s_mov_b32 s57, 0x800000
	v_and_b32_e32 v246, 0xff, v221
	v_lshlrev_b32_e32 v242, 4, v246
	v_mov_b32_e32 v243, 0
	v_lshl_add_u64 v[244:245], s[100:101], 0, v[242:243]
	v_add_u32_e32 v247, 0x13600, v242
	v_cmp_gt_u32_e32 vcc, 0x100, v221
	v_mov_b32_e32 v248, s26
	v_mov_b32_e32 v249, s27
	v_mov_b32_e32 v250, s24
	v_mov_b32_e32 v251, s25
	s_nop 1
	v_cndmask_b32_e32 v248, v248, v250, vcc
	v_cndmask_b32_e32 v249, v249, v251, vcc
	v_lshl_add_u64 v[242:243], v[248:249], 0, v[242:243]
	v_lshlrev_b32_e32 v246, 4, v221
	v_add_u32_e32 v246, 0x11600, v246
	v_and_b32_e32 v248, 15, v221
	v_lshlrev_b32_e32 v248, 5, v248
	v_add_u32_e32 v248, 0x11600, v248
	s_mov_b64 s[24:25], 0x10000
	v_mov_b32_e32 v201, 0x358637bd
	v_lshlrev_b32_e32 v202, 2, v0
	v_add_u32_e32 v249, 0x13600, v202
	s_mov_b32 s58, s10
	s_branch .LBB0_659
.LBB0_658:
	s_or_b64 exec, exec, s[4:5]
	s_waitcnt lgkmcnt(0)
	ds_read_b128 v[90:93], v249
	ds_read_b128 v[94:97], v249 offset:64
	ds_read_b128 v[98:101], v249 offset:512
	ds_read_b128 v[102:105], v249 offset:576
	ds_read_b128 v[106:109], v249 offset:1024
	ds_read_b128 v[110:113], v249 offset:1088
	ds_read_b128 v[114:117], v249 offset:1536
	ds_read_b128 v[138:141], v249 offset:1600
	ds_read_b128 v[142:145], v249 offset:2048
	ds_read_b128 v[146:149], v249 offset:2112
	ds_read_b128 v[150:153], v249 offset:2560
	ds_read_b128 v[222:225], v249 offset:2624
	ds_read_b128 v[226:229], v249 offset:3072
	ds_read_b128 v[230:233], v249 offset:3136
	ds_read_b128 v[234:237], v249 offset:3584
	ds_read_b128 v[238:241], v249 offset:3648
	s_barrier
; __device__ __forceinline__ unsigned cvt_pk_bf16(float lo, float hi) { unsigned r; asm volatile("v_cvt_pk_bf16_f32 %0, %1, %2" : "=v"(r) : "v"(lo), "v"(hi)); return r; }
; #define KIN(i) (*(const float* const __attribute__((address_space(4)))*)(kp + kz + 8 * (i)))
; __global__ void __launch_bounds__(NTHR, 2) fwd_megakernel(Args args) {
;     ...
;             ss += __shfl_xor(ss, 16); ss += __shfl_xor(ss, 32);
;             if (fq == 0) red[(mb * 4 + nq) * 16 + fr] = ss;
;             __syncthreads();
;             const float tot = (red[(mb * 4 + 0) * 16 + fr] + red[(mb * 4 + 1) * 16 + fr]) + (red[(mb * 4 + 2) * 16 + fr] + red[(mb * 4 + 3) * 16 + fr]);
;             const float r2 = rsqrtf(tot * (1.0f / CCH) + RMS_EPS);
; #pragma unroll
;             for (int h = 0; h < 8; ++h)
; #pragma unroll
;                 for (int nb = 0; nb < 2; ++nb) { const int ch = h * 128 + 32 * nq + 16 * nb + 4 * fq; const f32x4 gg = *(const f32x4*)(KIN(I_OUT_NORM_SGU) + ch); const f32x4 y = yv[h][nb] * r2 * gg;
;                     u32x2 w; w.x = cvt_pk_bf16(y[0], y[1]); w.y = cvt_pk_bf16(y[2], y[3]); *(u32x2*)(Y + (size_t)trow * D + CCH + ch) = w; }
	s_add_i32 s58, s58, s34
	s_add_i32 s23, s23, s56
	s_cmpk_lt_i32 s58, 0x100
	ds_read2_b32 v[72:73], v175 offset1:16
	ds_read2_b32 v[74:75], v175 offset0:32 offset1:48
	s_waitcnt lgkmcnt(1)
	v_mov_b32_e32 v78, v72
	s_waitcnt lgkmcnt(0)
	v_mov_b32_e32 v79, v74
	v_mov_b32_e32 v74, v73
	v_pk_add_f32 v[72:73], v[78:79], v[74:75]
	s_nop 0
	v_add_f32_e32 v72, v72, v73
	v_fmamk_f32 v72, v72, 0x3a800000, v201
	v_mul_f32_e32 v73, 0x4b800000, v72
	v_cmp_gt_f32_e32 vcc, s57, v72
	s_nop 1
	v_cndmask_b32_e32 v72, v72, v73, vcc
	v_rsq_f32_e32 v74, v72
	v_lshlrev_b64 v[72:73], 12, v[134:135]
	v_lshl_add_u64 v[72:73], v[132:133], 0, v[72:73]
	v_mul_f32_e32 v75, 0x45800000, v74
	v_cndmask_b32_e32 v74, v74, v75, vcc
	v_pk_mul_f32 v[0:1], v[74:75], v[14:15] op_sel_hi:[0,1]
	v_pk_mul_f32 v[2:3], v[74:75], v[12:13] op_sel_hi:[0,1]
	v_pk_mul_f32 v[0:1], v[90:91], v[0:1]
	v_pk_mul_f32 v[2:3], v[92:93], v[2:3]
	v_cvt_pk_bf16_f32 v0, v0, v1
	v_cvt_pk_bf16_f32 v1, v2, v3
	global_store_dwordx2 v[72:73], v[0:1], off offset:2048
	v_pk_mul_f32 v[4:5], v[74:75], v[10:11] op_sel_hi:[0,1]
	v_pk_mul_f32 v[6:7], v[74:75], v[8:9] op_sel_hi:[0,1]
	v_pk_mul_f32 v[4:5], v[94:95], v[4:5]
	v_pk_mul_f32 v[6:7], v[96:97], v[6:7]
	v_cvt_pk_bf16_f32 v4, v4, v5
	v_cvt_pk_bf16_f32 v5, v6, v7
	global_store_dwordx2 v[72:73], v[4:5], off offset:2080
	v_pk_mul_f32 v[0:1], v[74:75], v[80:81] op_sel_hi:[0,1]
	v_pk_mul_f32 v[2:3], v[74:75], v[20:21] op_sel_hi:[0,1]
	v_pk_mul_f32 v[0:1], v[98:99], v[0:1]
	v_pk_mul_f32 v[2:3], v[100:101], v[2:3]
	v_cvt_pk_bf16_f32 v0, v0, v1
	v_cvt_pk_bf16_f32 v1, v2, v3
	global_store_dwordx2 v[72:73], v[0:1], off offset:2304
	v_pk_mul_f32 v[4:5], v[74:75], v[18:19] op_sel_hi:[0,1]
	v_pk_mul_f32 v[6:7], v[74:75], v[16:17] op_sel_hi:[0,1]
	v_pk_mul_f32 v[4:5], v[102:103], v[4:5]
	v_pk_mul_f32 v[6:7], v[104:105], v[6:7]
	v_cvt_pk_bf16_f32 v4, v4, v5
	v_cvt_pk_bf16_f32 v5, v6, v7
	global_store_dwordx2 v[72:73], v[4:5], off offset:2336
	v_pk_mul_f32 v[0:1], v[74:75], v[30:31] op_sel_hi:[0,1]
	v_pk_mul_f32 v[2:3], v[74:75], v[28:29] op_sel_hi:[0,1]
	v_pk_mul_f32 v[0:1], v[106:107], v[0:1]
	v_pk_mul_f32 v[2:3], v[108:109], v[2:3]
	v_cvt_pk_bf16_f32 v0, v0, v1
	v_cvt_pk_bf16_f32 v1, v2, v3
	global_store_dwordx2 v[72:73], v[0:1], off offset:2560
	v_pk_mul_f32 v[4:5], v[74:75], v[24:25] op_sel_hi:[0,1]
	v_pk_mul_f32 v[6:7], v[74:75], v[22:23] op_sel_hi:[0,1]
	v_pk_mul_f32 v[4:5], v[110:111], v[4:5]
	v_pk_mul_f32 v[6:7], v[112:113], v[6:7]
	v_cvt_pk_bf16_f32 v4, v4, v5
	v_cvt_pk_bf16_f32 v5, v6, v7
	global_store_dwordx2 v[72:73], v[4:5], off offset:2592
	v_pk_mul_f32 v[0:1], v[74:75], v[46:47] op_sel_hi:[0,1]
	v_pk_mul_f32 v[2:3], v[74:75], v[44:45] op_sel_hi:[0,1]
	v_pk_mul_f32 v[0:1], v[114:115], v[0:1]
	v_pk_mul_f32 v[2:3], v[116:117], v[2:3]
	v_cvt_pk_bf16_f32 v0, v0, v1
	v_cvt_pk_bf16_f32 v1, v2, v3
	global_store_dwordx2 v[72:73], v[0:1], off offset:2816
	v_pk_mul_f32 v[4:5], v[74:75], v[40:41] op_sel_hi:[0,1]
	v_pk_mul_f32 v[6:7], v[74:75], v[26:27] op_sel_hi:[0,1]
	v_pk_mul_f32 v[4:5], v[138:139], v[4:5]
	v_pk_mul_f32 v[6:7], v[140:141], v[6:7]
	v_cvt_pk_bf16_f32 v4, v4, v5
	v_cvt_pk_bf16_f32 v5, v6, v7
	global_store_dwordx2 v[72:73], v[4:5], off offset:2848
	v_pk_mul_f32 v[0:1], v[74:75], v[82:83] op_sel_hi:[0,1]
	v_pk_mul_f32 v[2:3], v[74:75], v[52:53] op_sel_hi:[0,1]
	v_pk_mul_f32 v[0:1], v[142:143], v[0:1]
	v_pk_mul_f32 v[2:3], v[144:145], v[2:3]
	v_cvt_pk_bf16_f32 v0, v0, v1
	v_cvt_pk_bf16_f32 v1, v2, v3
	global_store_dwordx2 v[72:73], v[0:1], off offset:3072
	v_pk_mul_f32 v[4:5], v[74:75], v[48:49] op_sel_hi:[0,1]
	v_pk_mul_f32 v[6:7], v[74:75], v[42:43] op_sel_hi:[0,1]
	v_pk_mul_f32 v[4:5], v[146:147], v[4:5]
	v_pk_mul_f32 v[6:7], v[148:149], v[6:7]
	v_cvt_pk_bf16_f32 v4, v4, v5
	v_cvt_pk_bf16_f32 v5, v6, v7
	global_store_dwordx2 v[72:73], v[4:5], off offset:3104
	v_pk_mul_f32 v[0:1], v[74:75], v[84:85] op_sel_hi:[0,1]
	v_pk_mul_f32 v[2:3], v[74:75], v[60:61] op_sel_hi:[0,1]
	v_pk_mul_f32 v[0:1], v[150:151], v[0:1]
	v_pk_mul_f32 v[2:3], v[152:153], v[2:3]
	v_cvt_pk_bf16_f32 v0, v0, v1
	v_cvt_pk_bf16_f32 v1, v2, v3
	global_store_dwordx2 v[72:73], v[0:1], off offset:3328
	v_pk_mul_f32 v[4:5], v[74:75], v[58:59] op_sel_hi:[0,1]
	v_pk_mul_f32 v[6:7], v[74:75], v[54:55] op_sel_hi:[0,1]
	v_pk_mul_f32 v[4:5], v[222:223], v[4:5]
	v_pk_mul_f32 v[6:7], v[224:225], v[6:7]
	v_cvt_pk_bf16_f32 v4, v4, v5
	v_cvt_pk_bf16_f32 v5, v6, v7
	global_store_dwordx2 v[72:73], v[4:5], off offset:3360
	v_pk_mul_f32 v[0:1], v[74:75], v[70:71] op_sel_hi:[0,1]
	v_pk_mul_f32 v[2:3], v[74:75], v[68:69] op_sel_hi:[0,1]
	v_pk_mul_f32 v[0:1], v[226:227], v[0:1]
	v_pk_mul_f32 v[2:3], v[228:229], v[2:3]
	v_cvt_pk_bf16_f32 v0, v0, v1
	v_cvt_pk_bf16_f32 v1, v2, v3
	global_store_dwordx2 v[72:73], v[0:1], off offset:3584
	v_pk_mul_f32 v[4:5], v[74:75], v[64:65] op_sel_hi:[0,1]
	v_pk_mul_f32 v[6:7], v[74:75], v[62:63] op_sel_hi:[0,1]
	v_pk_mul_f32 v[4:5], v[230:231], v[4:5]
	v_pk_mul_f32 v[6:7], v[232:233], v[6:7]
	v_cvt_pk_bf16_f32 v4, v4, v5
	v_cvt_pk_bf16_f32 v5, v6, v7
	global_store_dwordx2 v[72:73], v[4:5], off offset:3616
	v_pk_mul_f32 v[0:1], v[74:75], v[76:77] op_sel_hi:[0,1]
	v_pk_mul_f32 v[2:3], v[74:75], v[66:67] op_sel_hi:[0,1]
	v_pk_mul_f32 v[0:1], v[234:235], v[0:1]
	v_pk_mul_f32 v[2:3], v[236:237], v[2:3]
	v_cvt_pk_bf16_f32 v0, v0, v1
	v_cvt_pk_bf16_f32 v1, v2, v3
	global_store_dwordx2 v[72:73], v[0:1], off offset:3840
	v_pk_mul_f32 v[4:5], v[74:75], v[56:57] op_sel_hi:[0,1]
	v_pk_mul_f32 v[6:7], v[74:75], v[50:51] op_sel_hi:[0,1]
	v_pk_mul_f32 v[4:5], v[238:239], v[4:5]
	v_pk_mul_f32 v[6:7], v[240:241], v[6:7]
	v_cvt_pk_bf16_f32 v4, v4, v5
	v_cvt_pk_bf16_f32 v5, v6, v7
	global_store_dwordx2 v[72:73], v[4:5], off offset:3872
	s_barrier
	s_cbranch_scc0 .LBB0_775
; __global__ void __launch_bounds__(NTHR, 2) fwd_megakernel(Args args) {
;     ...
;             if (tid < J) { const f32x4* p = (const f32x4*)(VSTAT + (size_t)(tc0 + tid) * 32); float s1 = 0.f, s2 = 0.f;
; #pragma unroll
;                 for (int j = 0; j < 8; ++j) { const f32x4 v = p[j]; s1 += v[0] + v[2]; s2 += v[1] + v[3]; }
;                 const float mean = s1 * (1.0f / CCH), var = fmaxf(s2 * (1.0f / CCH) - mean * mean, 0.f); st[tid] = (f32x2){mean, rsqrtf(var + LN_EPS)}; }
.LBB0_659:
	global_load_dwordx4 v[250:253], v[242:243], off
	global_load_dwordx4 v[212:215], v[244:245], off
	s_and_b32 s11, s23, 0xffffff80
	s_and_b32 s44, s58, 3
	s_cmp_gt_u32 s44, 1
	s_cselect_b64 s[26:27], -1, 0
	s_and_b64 s[4:5], s[26:27], exec
	s_cselect_b32 s4, 0x80, 64
	v_cmp_gt_u32_e32 vcc, s4, v221
	s_and_saveexec_b64 s[4:5], vcc
	s_cbranch_execz .LBB0_661
	v_add_u32_e32 v8, s11, v221
	v_ashrrev_i32_e32 v9, 31, v8
	v_lshlrev_b64 v[8:9], 7, v[8:9]
	v_lshl_add_u64 v[44:45], s[38:39], 0, v[8:9]
	global_load_dwordx4 v[8:11], v[44:45], off
	global_load_dwordx4 v[12:15], v[44:45], off offset:16
	global_load_dwordx4 v[16:19], v[44:45], off offset:32
	global_load_dwordx4 v[20:23], v[44:45], off offset:48
	global_load_dwordx4 v[24:27], v[44:45], off offset:64
	global_load_dwordx4 v[28:31], v[44:45], off offset:80
	global_load_dwordx4 v[40:43], v[44:45], off offset:96
	s_nop 0
	global_load_dwordx4 v[44:47], v[44:45], off offset:112
	s_waitcnt vmcnt(7)
	v_pk_add_f32 v[8:9], v[8:9], v[10:11]
	s_waitcnt vmcnt(6)
	v_pk_add_f32 v[10:11], v[12:13], v[14:15]
	v_pk_add_f32 v[8:9], v[8:9], 0 op_sel_hi:[1,0]
	s_waitcnt vmcnt(5)
	v_pk_add_f32 v[12:13], v[16:17], v[18:19]
	v_pk_add_f32 v[8:9], v[8:9], v[10:11]
	s_waitcnt vmcnt(4)
	v_pk_add_f32 v[14:15], v[20:21], v[22:23]
	v_pk_add_f32 v[8:9], v[8:9], v[12:13]
	s_waitcnt vmcnt(3)
	v_pk_add_f32 v[16:17], v[24:25], v[26:27]
	v_pk_add_f32 v[8:9], v[8:9], v[14:15]
	s_waitcnt vmcnt(2)
	v_pk_add_f32 v[18:19], v[28:29], v[30:31]
	v_pk_add_f32 v[8:9], v[8:9], v[16:17]
	s_waitcnt vmcnt(1)
	v_pk_add_f32 v[20:21], v[40:41], v[42:43]
	v_pk_add_f32 v[8:9], v[8:9], v[18:19]
	s_waitcnt vmcnt(0)
	v_pk_add_f32 v[22:23], v[44:45], v[46:47]
	v_pk_add_f32 v[8:9], v[8:9], v[20:21]
	s_nop 0
	v_pk_add_f32 v[8:9], v[8:9], v[22:23]
	s_nop 0
	v_pk_mul_f32 v[8:9], v[8:9], s[22:23] op_sel_hi:[1,0]
	s_nop 0
	v_fma_f32 v9, -v8, v8, v9
	v_max_f32_e32 v9, 0, v9
	v_add_f32_e32 v9, 0x3727c5ac, v9
	v_mul_f32_e32 v10, 0x4b800000, v9
	v_cmp_gt_f32_e32 vcc, s57, v9
	s_nop 1
	v_cndmask_b32_e32 v9, v9, v10, vcc
	v_rsq_f32_e32 v9, v9
	s_nop 0
	v_mul_f32_e32 v10, 0x45800000, v9
	v_cndmask_b32_e32 v9, v9, v10, vcc
	ds_write_b64 v137, v[8:9]

; __global__ void __launch_bounds__(NTHR, 2) fwd_megakernel(Args args) {
;     ...
;             f32x4 yv[8][2]; float ss = 0.f;
;             SGU_PREFETCH(0);
.LBB0_665:
	v_lshl_or_b32 v48, s44, 5, v155
	s_nop 0
	s_nop 0
	s_nop 0
	s_nop 0
	v_lshlrev_b32_e32 v120, 8, v48
	v_lshl_add_u64 v[148:149], v[128:129], 0, v[120:121]
	global_load_dwordx4 v[12:15], v[148:149], off
	global_load_dwordx4 v[8:11], v[148:149], off offset:64
	s_and_b64 vcc, exec, s[4:5]
	s_cbranch_vccnz .LBB0_667
	global_load_dwordx4 v[36:39], v[148:149], off offset:128

; #define LAS __attribute__((address_space(3)))
; __device__ __forceinline__ unsigned cvt_pk_bf16(float lo, float hi) { unsigned r; asm volatile("v_cvt_pk_bf16_f32 %0, %1, %2" : "=v"(r) : "v"(lo), "v"(hi)); return r; }
; __device__ __forceinline__ float bf_lo(unsigned u) { return __uint_as_float(u << 16); }
; __device__ __forceinline__ float bf_hi(unsigned u) { return __uint_as_float(u & 0xffff0000u); }
; __global__ void __launch_bounds__(NTHR, 2) fwd_megakernel(Args args) {
;     ...
;             f32x4 yv[8][2]; float ss = 0.f;
;             SGU_PREFETCH(0);
;             __syncthreads();
; #pragma unroll
;             for (int h = 0; h < 8; ++h) {
;                 LAS bf16_t* Bc = Bt + (h & 1) * (128 * LDB);
; #pragma unroll
;                 for (int k = 0; k < 4; ++k) if (k < nk) { const int j = jb + 32 * k; const u32x4 v = pv[k]; const f32x2 ms = st[j];
;                     const f32x4 x0 = (f32x4){bf_lo(v.x), bf_hi(v.x), bf_lo(v.y), bf_hi(v.y)}, x1 = (f32x4){bf_lo(v.z), bf_hi(v.z), bf_lo(v.w), bf_hi(v.w)};
;                     const f32x4 y0 = (x0 - ms.x) * ms.y * pg0 + pb0, y1 = (x1 - ms.x) * ms.y * pg1 + pb1;
;                     LAS bf16_t* d = Bc + (c8 * 8) * LDB + (j ^ (8 * c8));
;                     const unsigned p0 = cvt_pk_bf16(y0[0], y0[1]), p1 = cvt_pk_bf16(y0[2], y0[3]), p2 = cvt_pk_bf16(y1[0], y1[1]), p3 = cvt_pk_bf16(y1[2], y1[3]);
;                     d[0 * LDB] = (bf16_t)(p0 & 0xffffu); d[1 * LDB] = (bf16_t)(p0 >> 16); d[2 * LDB] = (bf16_t)(p1 & 0xffffu); d[3 * LDB] = (bf16_t)(p1 >> 16);
;                     d[4 * LDB] = (bf16_t)(p2 & 0xffffu); d[5 * LDB] = (bf16_t)(p2 >> 16); d[6 * LDB] = (bf16_t)(p3 & 0xffffu); d[7 * LDB] = (bf16_t)(p3 >> 16); }
.LBB0_669:
	v_or_b32_e32 v134, s11, v48
	v_ashrrev_i32_e32 v135, 31, v134
	v_lshlrev_b32_e32 v120, 2, v48
	v_lshlrev_b64 v[48:49], 11, v[134:135]
	v_lshl_add_u64 v[150:151], v[130:131], 0, v[48:49]
	global_load_dword v136, v120, s[20:21]
	global_load_dwordx2 v[140:141], v[150:151], off
	global_load_dwordx2 v[138:139], v[150:151], off offset:32
	s_waitcnt vmcnt(7)
	ds_write_b128 v246, v[250:253]
	ds_write_b128 v247, v[212:215]
	s_waitcnt lgkmcnt(0)
	s_barrier
	ds_read_b128 v[16:19], v248 offset:16
	ds_read_b128 v[24:27], v248
	ds_read_b128 v[20:23], v248 offset:4112
	ds_read_b128 v[28:31], v248 offset:4096
	ds_read_b64 v[48:49], v181
	s_waitcnt vmcnt(6)
	v_lshlrev_b32_e32 v50, 16, v44
	v_and_b32_e32 v51, 0xffff0000, v44
	v_lshlrev_b32_e32 v44, 16, v45
	v_and_b32_e32 v45, 0xffff0000, v45
	v_lshlrev_b32_e32 v52, 16, v46
	v_and_b32_e32 v53, 0xffff0000, v46
	v_lshlrev_b32_e32 v54, 16, v47
	v_and_b32_e32 v55, 0xffff0000, v47
	s_waitcnt lgkmcnt(0)
	v_sub_f32_e32 v47, v51, v48
	v_sub_f32_e32 v46, v50, v48
	v_sub_f32_e32 v45, v45, v48
	v_sub_f32_e32 v44, v44, v48
	v_pk_mul_f32 v[46:47], v[48:49], v[46:47] op_sel:[1,0]
	v_pk_mul_f32 v[44:45], v[48:49], v[44:45] op_sel:[1,0]
	s_waitcnt vmcnt(5)
	v_pk_fma_f32 v[46:47], v[24:25], v[46:47], v[28:29]
	v_sub_f32_e32 v51, v55, v48
	v_sub_f32_e32 v50, v54, v48
	v_sub_f32_e32 v53, v53, v48
	v_sub_f32_e32 v52, v52, v48
	v_pk_fma_f32 v[44:45], v[26:27], v[44:45], v[30:31]
	v_pk_mul_f32 v[52:53], v[48:49], v[52:53] op_sel:[1,0]
	v_pk_mul_f32 v[48:49], v[48:49], v[50:51] op_sel:[1,0]
	v_cvt_pk_bf16_f32 v46, v46, v47
	v_pk_fma_f32 v[50:51], v[16:17], v[52:53], v[20:21]
	v_pk_fma_f32 v[48:49], v[18:19], v[48:49], v[22:23]
	v_cvt_pk_bf16_f32 v44, v44, v45
	v_cvt_pk_bf16_f32 v45, v50, v51
	v_lshlrev_b32_e32 v50, 16, v43
	v_cvt_pk_bf16_f32 v47, v48, v49
	ds_write_b16 v186, v46
	ds_write_b16_d16_hi v186, v46 offset:272
	ds_write_b16 v186, v44 offset:544
	ds_write_b16_d16_hi v186, v44 offset:816
	ds_write_b16 v186, v45 offset:1088
	ds_write_b16_d16_hi v186, v45 offset:1360
	ds_write_b16 v186, v47 offset:1632
	ds_write_b16_d16_hi v186, v47 offset:1904
	ds_read_b64 v[44:45], v187
	v_lshlrev_b32_e32 v46, 16, v40
	v_and_b32_e32 v47, 0xffff0000, v40
	v_lshlrev_b32_e32 v40, 16, v41
	v_and_b32_e32 v41, 0xffff0000, v41
	v_lshlrev_b32_e32 v48, 16, v42
	v_and_b32_e32 v49, 0xffff0000, v42
	v_and_b32_e32 v51, 0xffff0000, v43
	s_waitcnt lgkmcnt(0)
	v_sub_f32_e32 v43, v47, v44
	v_sub_f32_e32 v42, v46, v44
	v_sub_f32_e32 v41, v41, v44
	v_sub_f32_e32 v40, v40, v44
	v_pk_mul_f32 v[42:43], v[44:45], v[42:43] op_sel:[1,0]
	v_pk_mul_f32 v[40:41], v[44:45], v[40:41] op_sel:[1,0]
	v_pk_fma_f32 v[42:43], v[24:25], v[42:43], v[28:29]
	v_sub_f32_e32 v47, v51, v44
	v_sub_f32_e32 v46, v50, v44
	v_sub_f32_e32 v49, v49, v44
	v_sub_f32_e32 v48, v48, v44
	v_pk_fma_f32 v[40:41], v[26:27], v[40:41], v[30:31]
	v_pk_mul_f32 v[48:49], v[44:45], v[48:49] op_sel:[1,0]
	v_pk_mul_f32 v[44:45], v[44:45], v[46:47] op_sel:[1,0]
	v_cvt_pk_bf16_f32 v42, v42, v43
	s_and_b64 vcc, exec, s[4:5]
	v_pk_fma_f32 v[44:45], v[18:19], v[44:45], v[22:23]
	v_pk_fma_f32 v[46:47], v[16:17], v[48:49], v[20:21]
	v_cvt_pk_bf16_f32 v40, v40, v41
	s_nop 0
	v_cvt_pk_bf16_f32 v41, v46, v47
	v_cvt_pk_bf16_f32 v43, v44, v45
	ds_write_b16 v188, v42
	ds_write_b16_d16_hi v188, v42 offset:272
	ds_write_b16 v188, v40 offset:544
	ds_write_b16_d16_hi v188, v40 offset:816
	ds_write_b16 v188, v41 offset:1088
	ds_write_b16_d16_hi v188, v41 offset:1360
	ds_write_b16 v188, v43 offset:1632
	ds_write_b16_d16_hi v188, v43 offset:1904
	s_cbranch_vccnz .LBB0_671
	ds_read_b64 v[40:41], v189
	v_lshlrev_b32_e32 v44, 16, v0
	v_and_b32_e32 v45, 0xffff0000, v0
	v_lshlrev_b32_e32 v42, 16, v1
	v_and_b32_e32 v43, 0xffff0000, v1
	v_lshlrev_b32_e32 v48, 16, v2
	v_and_b32_e32 v49, 0xffff0000, v2
	v_lshlrev_b32_e32 v46, 16, v3
	v_and_b32_e32 v47, 0xffff0000, v3
	s_waitcnt lgkmcnt(0)
	v_sub_f32_e32 v45, v45, v40
	v_sub_f32_e32 v44, v44, v40
	v_sub_f32_e32 v43, v43, v40
	v_sub_f32_e32 v42, v42, v40
	v_pk_mul_f32 v[44:45], v[40:41], v[44:45] op_sel:[1,0]
	v_sub_f32_e32 v47, v47, v40
	v_sub_f32_e32 v46, v46, v40
	v_sub_f32_e32 v49, v49, v40
	v_sub_f32_e32 v48, v48, v40
	v_pk_mul_f32 v[42:43], v[40:41], v[42:43] op_sel:[1,0]
	v_pk_fma_f32 v[44:45], v[24:25], v[44:45], v[28:29]
	v_pk_mul_f32 v[48:49], v[40:41], v[48:49] op_sel:[1,0]
	v_pk_mul_f32 v[40:41], v[40:41], v[46:47] op_sel:[1,0]
	v_pk_fma_f32 v[42:43], v[26:27], v[42:43], v[30:31]
	v_pk_fma_f32 v[40:41], v[18:19], v[40:41], v[22:23]
	v_cvt_pk_bf16_f32 v44, v44, v45
	v_pk_fma_f32 v[46:47], v[16:17], v[48:49], v[20:21]
	v_cvt_pk_bf16_f32 v42, v42, v43
	v_and_b32_e32 v45, 0xffff0000, v4
	v_cvt_pk_bf16_f32 v43, v46, v47
	v_cvt_pk_bf16_f32 v40, v40, v41
	ds_write_b16 v190, v44
	ds_write_b16_d16_hi v190, v44 offset:272
	ds_write_b16 v190, v42 offset:544
	ds_write_b16_d16_hi v190, v42 offset:816
	ds_write_b16 v190, v43 offset:1088
	ds_write_b16_d16_hi v190, v43 offset:1360
	ds_write_b16 v190, v40 offset:1632
	ds_write_b16_d16_hi v190, v40 offset:1904
	ds_read_b64 v[40:41], v191
	v_lshlrev_b32_e32 v42, 16, v5
	v_and_b32_e32 v43, 0xffff0000, v5
	v_lshlrev_b32_e32 v44, 16, v4
	v_lshlrev_b32_e32 v46, 16, v6
	s_waitcnt lgkmcnt(0)
	v_sub_f32_e32 v43, v43, v40
	v_sub_f32_e32 v42, v42, v40
	v_and_b32_e32 v47, 0xffff0000, v6
	v_sub_f32_e32 v45, v45, v40
	v_sub_f32_e32 v44, v44, v40
	v_pk_mul_f32 v[42:43], v[40:41], v[42:43] op_sel:[1,0]
	v_lshlrev_b32_e32 v48, 16, v7
	v_and_b32_e32 v49, 0xffff0000, v7
	v_pk_mul_f32 v[44:45], v[40:41], v[44:45] op_sel:[1,0]
	v_pk_fma_f32 v[26:27], v[26:27], v[42:43], v[30:31]
	v_sub_f32_e32 v31, v47, v40
	v_sub_f32_e32 v30, v46, v40
	v_pk_fma_f32 v[24:25], v[24:25], v[44:45], v[28:29]
	v_sub_f32_e32 v29, v49, v40
	v_sub_f32_e32 v28, v48, v40
	v_pk_mul_f32 v[30:31], v[40:41], v[30:31] op_sel:[1,0]
	v_pk_mul_f32 v[28:29], v[40:41], v[28:29] op_sel:[1,0]
	v_pk_fma_f32 v[16:17], v[16:17], v[30:31], v[20:21]
	v_cvt_pk_bf16_f32 v20, v24, v25
	v_pk_fma_f32 v[18:19], v[18:19], v[28:29], v[22:23]
	v_cvt_pk_bf16_f32 v21, v26, v27
	v_cvt_pk_bf16_f32 v16, v16, v17
	s_nop 0
	v_cvt_pk_bf16_f32 v17, v18, v19
	ds_write_b16 v192, v20
	ds_write_b16_d16_hi v192, v20 offset:272
	ds_write_b16 v192, v21 offset:544
	ds_write_b16_d16_hi v192, v21 offset:816
	ds_write_b16 v192, v16 offset:1088
	ds_write_b16_d16_hi v192, v16 offset:1360
	ds_write_b16 v192, v17 offset:1632
	ds_write_b16_d16_hi v192, v17 offset:1904

.LBB0_675:
	s_nop 0
	ds_read_b128 v[40:43], v248 offset:528
	ds_read_b128 v[48:51], v248 offset:512
	ds_read_b128 v[44:47], v248 offset:4624
	ds_read_b128 v[52:55], v248 offset:4608
	v_add_co_u32_e32 v16, vcc, 0x8000, v148
	s_waitcnt vmcnt(5)
	v_mov_b64_e32 v[28:29], v[36:37]
	v_addc_co_u32_e32 v17, vcc, 0, v149, vcc
	global_load_dwordx4 v[20:23], v[16:17], off
	s_nop 0
	global_load_dwordx4 v[16:19], v[16:17], off offset:64
	s_and_b64 vcc, exec, s[4:5]
	v_mov_b64_e32 v[30:31], v[38:39]
	s_cbranch_vccnz .LBB0_677
	v_add_co_u32_e32 v24, vcc, 0x8000, v148
	s_nop 1
	v_addc_co_u32_e32 v25, vcc, 0, v149, vcc
	global_load_dwordx4 v[28:31], v[24:25], off offset:128

; #define LAS __attribute__((address_space(3)))
; __device__ __forceinline__ unsigned cvt_pk_bf16(float lo, float hi) { unsigned r; asm volatile("v_cvt_pk_bf16_f32 %0, %1, %2" : "=v"(r) : "v"(lo), "v"(hi)); return r; }
; __device__ __forceinline__ float bf_lo(unsigned u) { return __uint_as_float(u << 16); }
; __device__ __forceinline__ float bf_hi(unsigned u) { return __uint_as_float(u & 0xffff0000u); }
; __global__ void __launch_bounds__(NTHR, 2) fwd_megakernel(Args args) {
;     ...
;                 for (int k = 0; k < 4; ++k) if (k < nk) { const int j = jb + 32 * k; const u32x4 v = pv[k]; const f32x2 ms = st[j];
;                     const f32x4 x0 = (f32x4){bf_lo(v.x), bf_hi(v.x), bf_lo(v.y), bf_hi(v.y)}, x1 = (f32x4){bf_lo(v.z), bf_hi(v.z), bf_lo(v.w), bf_hi(v.w)};
;                     const f32x4 y0 = (x0 - ms.x) * ms.y * pg0 + pb0, y1 = (x1 - ms.x) * ms.y * pg1 + pb1;
;                     LAS bf16_t* d = Bc + (c8 * 8) * LDB + (j ^ (8 * c8));
;                     const unsigned p0 = cvt_pk_bf16(y0[0], y0[1]), p1 = cvt_pk_bf16(y0[2], y0[3]), p2 = cvt_pk_bf16(y1[0], y1[1]), p3 = cvt_pk_bf16(y1[2], y1[3]);
;                     d[0 * LDB] = (bf16_t)(p0 & 0xffffu); d[1 * LDB] = (bf16_t)(p0 >> 16); d[2 * LDB] = (bf16_t)(p1 & 0xffffu); d[3 * LDB] = (bf16_t)(p1 >> 16);
;                     d[4 * LDB] = (bf16_t)(p2 & 0xffffu); d[5 * LDB] = (bf16_t)(p2 >> 16); d[6 * LDB] = (bf16_t)(p3 & 0xffffu); d[7 * LDB] = (bf16_t)(p3 >> 16); }
.LBB0_683:
	ds_read_b64 v[32:33], v181
	s_waitcnt vmcnt(6)
	v_lshlrev_b32_e32 v36, 16, v60
	v_and_b32_e32 v37, 0xffff0000, v60
	v_lshlrev_b32_e32 v34, 16, v61
	v_and_b32_e32 v35, 0xffff0000, v61
	v_lshlrev_b32_e32 v60, 16, v62
	v_and_b32_e32 v61, 0xffff0000, v62
	v_lshlrev_b32_e32 v38, 16, v63
	v_and_b32_e32 v39, 0xffff0000, v63
	s_waitcnt lgkmcnt(0)
	v_sub_f32_e32 v37, v37, v32
	v_sub_f32_e32 v36, v36, v32
	v_sub_f32_e32 v35, v35, v32
	v_sub_f32_e32 v34, v34, v32
	v_pk_mul_f32 v[36:37], v[32:33], v[36:37] op_sel:[1,0]
	v_sub_f32_e32 v39, v39, v32
	v_sub_f32_e32 v38, v38, v32
	v_sub_f32_e32 v61, v61, v32
	v_sub_f32_e32 v60, v60, v32
	v_pk_mul_f32 v[34:35], v[32:33], v[34:35] op_sel:[1,0]
	s_waitcnt vmcnt(5)
	v_pk_fma_f32 v[36:37], v[48:49], v[36:37], v[52:53]
	v_pk_mul_f32 v[60:61], v[32:33], v[60:61] op_sel:[1,0]
	v_pk_mul_f32 v[32:33], v[32:33], v[38:39] op_sel:[1,0]
	v_pk_fma_f32 v[34:35], v[50:51], v[34:35], v[54:55]
	v_pk_fma_f32 v[32:33], v[42:43], v[32:33], v[46:47]
	v_cvt_pk_bf16_f32 v36, v36, v37
	v_pk_fma_f32 v[38:39], v[40:41], v[60:61], v[44:45]
	v_cvt_pk_bf16_f32 v34, v34, v35
	v_and_b32_e32 v37, 0xffff0000, v56
	v_cvt_pk_bf16_f32 v35, v38, v39
	v_cvt_pk_bf16_f32 v32, v32, v33
	ds_write_b16 v186, v36 offset:34816
	ds_write_b16_d16_hi v186, v36 offset:35088
	ds_write_b16 v186, v34 offset:35360
	ds_write_b16_d16_hi v186, v34 offset:35632
	ds_write_b16 v186, v35 offset:35904
	ds_write_b16_d16_hi v186, v35 offset:36176
	ds_write_b16 v186, v32 offset:36448
	ds_write_b16_d16_hi v186, v32 offset:36720
	ds_read_b64 v[32:33], v187
	v_lshlrev_b32_e32 v36, 16, v56
	v_lshlrev_b32_e32 v34, 16, v57
	v_and_b32_e32 v35, 0xffff0000, v57
	v_lshlrev_b32_e32 v56, 16, v58
	v_and_b32_e32 v57, 0xffff0000, v58
	v_lshlrev_b32_e32 v38, 16, v59
	v_and_b32_e32 v39, 0xffff0000, v59
	s_waitcnt lgkmcnt(0)
	v_sub_f32_e32 v37, v37, v32
	v_sub_f32_e32 v36, v36, v32
	v_sub_f32_e32 v35, v35, v32
	v_sub_f32_e32 v34, v34, v32
	v_pk_mul_f32 v[36:37], v[32:33], v[36:37] op_sel:[1,0]
	v_sub_f32_e32 v39, v39, v32
	v_sub_f32_e32 v38, v38, v32
	v_sub_f32_e32 v57, v57, v32
	v_sub_f32_e32 v56, v56, v32
	v_pk_mul_f32 v[34:35], v[32:33], v[34:35] op_sel:[1,0]
	v_pk_fma_f32 v[36:37], v[48:49], v[36:37], v[52:53]
	v_pk_mul_f32 v[56:57], v[32:33], v[56:57] op_sel:[1,0]
	v_pk_mul_f32 v[32:33], v[32:33], v[38:39] op_sel:[1,0]
	v_pk_fma_f32 v[34:35], v[50:51], v[34:35], v[54:55]
	v_pk_fma_f32 v[32:33], v[42:43], v[32:33], v[46:47]
	v_cvt_pk_bf16_f32 v36, v36, v37
	s_and_b64 vcc, exec, s[4:5]
	v_pk_fma_f32 v[38:39], v[40:41], v[56:57], v[44:45]
	v_cvt_pk_bf16_f32 v34, v34, v35
	s_nop 0
	v_cvt_pk_bf16_f32 v35, v38, v39
	v_cvt_pk_bf16_f32 v32, v32, v33
	ds_write_b16 v188, v36 offset:34816
	ds_write_b16_d16_hi v188, v36 offset:35088
	ds_write_b16 v188, v34 offset:35360
	ds_write_b16_d16_hi v188, v34 offset:35632
	ds_write_b16 v188, v35 offset:35904
	ds_write_b16_d16_hi v188, v35 offset:36176
	ds_write_b16 v188, v32 offset:36448
	ds_write_b16_d16_hi v188, v32 offset:36720
	s_cbranch_vccnz .LBB0_685
	ds_read_b64 v[32:33], v189
	v_lshlrev_b32_e32 v36, 16, v0
	v_and_b32_e32 v37, 0xffff0000, v0
	v_lshlrev_b32_e32 v34, 16, v1
	v_and_b32_e32 v35, 0xffff0000, v1
	v_lshlrev_b32_e32 v56, 16, v2
	v_and_b32_e32 v57, 0xffff0000, v2
	v_lshlrev_b32_e32 v38, 16, v3
	v_and_b32_e32 v39, 0xffff0000, v3
	s_waitcnt lgkmcnt(0)
	v_sub_f32_e32 v37, v37, v32
	v_sub_f32_e32 v36, v36, v32
	v_sub_f32_e32 v35, v35, v32
	v_sub_f32_e32 v34, v34, v32
	v_pk_mul_f32 v[36:37], v[32:33], v[36:37] op_sel:[1,0]
	v_sub_f32_e32 v39, v39, v32
	v_sub_f32_e32 v38, v38, v32
	v_sub_f32_e32 v57, v57, v32
	v_sub_f32_e32 v56, v56, v32
	v_pk_mul_f32 v[34:35], v[32:33], v[34:35] op_sel:[1,0]
	v_pk_fma_f32 v[36:37], v[48:49], v[36:37], v[52:53]
	v_pk_mul_f32 v[56:57], v[32:33], v[56:57] op_sel:[1,0]
	v_pk_mul_f32 v[32:33], v[32:33], v[38:39] op_sel:[1,0]
	v_pk_fma_f32 v[34:35], v[50:51], v[34:35], v[54:55]
	v_pk_fma_f32 v[32:33], v[42:43], v[32:33], v[46:47]
	v_cvt_pk_bf16_f32 v36, v36, v37
	v_pk_fma_f32 v[38:39], v[40:41], v[56:57], v[44:45]
	v_cvt_pk_bf16_f32 v34, v34, v35
	v_and_b32_e32 v37, 0xffff0000, v4
	v_cvt_pk_bf16_f32 v35, v38, v39
	v_cvt_pk_bf16_f32 v32, v32, v33
	ds_write_b16 v190, v36 offset:34816
	ds_write_b16_d16_hi v190, v36 offset:35088
	ds_write_b16 v190, v34 offset:35360
	ds_write_b16_d16_hi v190, v34 offset:35632
	ds_write_b16 v190, v35 offset:35904
	ds_write_b16_d16_hi v190, v35 offset:36176
	ds_write_b16 v190, v32 offset:36448
	ds_write_b16_d16_hi v190, v32 offset:36720
	ds_read_b64 v[32:33], v191
	v_lshlrev_b32_e32 v36, 16, v4
	v_lshlrev_b32_e32 v34, 16, v5
	v_and_b32_e32 v35, 0xffff0000, v5
	v_lshlrev_b32_e32 v56, 16, v6
	s_waitcnt lgkmcnt(0)
	v_sub_f32_e32 v37, v37, v32
	v_sub_f32_e32 v36, v36, v32
	v_and_b32_e32 v57, 0xffff0000, v6
	v_lshlrev_b32_e32 v38, 16, v7
	v_and_b32_e32 v39, 0xffff0000, v7
	v_pk_mul_f32 v[36:37], v[32:33], v[36:37] op_sel:[1,0]
	v_sub_f32_e32 v35, v35, v32
	v_sub_f32_e32 v34, v34, v32
	v_pk_fma_f32 v[36:37], v[48:49], v[36:37], v[52:53]
	v_sub_f32_e32 v39, v39, v32
	v_sub_f32_e32 v38, v38, v32
	v_sub_f32_e32 v49, v57, v32
	v_sub_f32_e32 v48, v56, v32
	v_pk_mul_f32 v[34:35], v[32:33], v[34:35] op_sel:[1,0]
	v_pk_mul_f32 v[48:49], v[32:33], v[48:49] op_sel:[1,0]
	v_pk_mul_f32 v[32:33], v[32:33], v[38:39] op_sel:[1,0]
	v_pk_fma_f32 v[34:35], v[50:51], v[34:35], v[54:55]
	v_pk_fma_f32 v[32:33], v[42:43], v[32:33], v[46:47]
	v_cvt_pk_bf16_f32 v36, v36, v37
	v_pk_fma_f32 v[38:39], v[40:41], v[48:49], v[44:45]
	v_cvt_pk_bf16_f32 v34, v34, v35
	s_nop 0
	v_cvt_pk_bf16_f32 v35, v38, v39
	v_cvt_pk_bf16_f32 v32, v32, v33
	ds_write_b16 v192, v36 offset:34816
	ds_write_b16_d16_hi v192, v36 offset:35088
	ds_write_b16 v192, v34 offset:35360
	ds_write_b16_d16_hi v192, v34 offset:35632
	ds_write_b16 v192, v35 offset:35904
	ds_write_b16_d16_hi v192, v35 offset:36176
	ds_write_b16 v192, v32 offset:36448
	ds_write_b16_d16_hi v192, v32 offset:36720

.LBB0_689:
	s_nop 0
	ds_read_b128 v[36:39], v248 offset:1040
	ds_read_b128 v[52:55], v248 offset:1024
	ds_read_b128 v[48:51], v248 offset:5136
	ds_read_b128 v[60:63], v248 offset:5120
	v_add_co_u32_e32 v32, vcc, 0x10000, v148
	s_waitcnt vmcnt(5)
	v_mov_b64_e32 v[46:47], v[30:31]
	v_addc_co_u32_e32 v33, vcc, 0, v149, vcc
	global_load_dwordx4 v[56:59], v[32:33], off
	global_load_dwordx4 v[40:43], v[32:33], off offset:64
	s_and_b64 vcc, exec, s[4:5]
	v_mov_b64_e32 v[44:45], v[28:29]
	s_cbranch_vccnz .LBB0_691
	v_add_co_u32_e32 v32, vcc, 0x10000, v148
	s_nop 1
	v_addc_co_u32_e32 v33, vcc, 0, v149, vcc
	global_load_dwordx4 v[44:47], v[32:33], off offset:128

; #define LAS __attribute__((address_space(3)))
; __device__ __forceinline__ unsigned cvt_pk_bf16(float lo, float hi) { unsigned r; asm volatile("v_cvt_pk_bf16_f32 %0, %1, %2" : "=v"(r) : "v"(lo), "v"(hi)); return r; }
; __device__ __forceinline__ float bf_lo(unsigned u) { return __uint_as_float(u << 16); }
; __device__ __forceinline__ float bf_hi(unsigned u) { return __uint_as_float(u & 0xffff0000u); }
; __global__ void __launch_bounds__(NTHR, 2) fwd_megakernel(Args args) {
;     ...
;                 for (int k = 0; k < 4; ++k) if (k < nk) { const int j = jb + 32 * k; const u32x4 v = pv[k]; const f32x2 ms = st[j];
;                     const f32x4 x0 = (f32x4){bf_lo(v.x), bf_hi(v.x), bf_lo(v.y), bf_hi(v.y)}, x1 = (f32x4){bf_lo(v.z), bf_hi(v.z), bf_lo(v.w), bf_hi(v.w)};
;                     const f32x4 y0 = (x0 - ms.x) * ms.y * pg0 + pb0, y1 = (x1 - ms.x) * ms.y * pg1 + pb1;
;                     LAS bf16_t* d = Bc + (c8 * 8) * LDB + (j ^ (8 * c8));
;                     const unsigned p0 = cvt_pk_bf16(y0[0], y0[1]), p1 = cvt_pk_bf16(y0[2], y0[3]), p2 = cvt_pk_bf16(y1[0], y1[1]), p3 = cvt_pk_bf16(y1[2], y1[3]);
;                     d[0 * LDB] = (bf16_t)(p0 & 0xffffu); d[1 * LDB] = (bf16_t)(p0 >> 16); d[2 * LDB] = (bf16_t)(p1 & 0xffffu); d[3 * LDB] = (bf16_t)(p1 >> 16);
;                     d[4 * LDB] = (bf16_t)(p2 & 0xffffu); d[5 * LDB] = (bf16_t)(p2 >> 16); d[6 * LDB] = (bf16_t)(p3 & 0xffffu); d[7 * LDB] = (bf16_t)(p3 >> 16); }
.LBB0_697:
	ds_read_b64 v[24:25], v181
	s_waitcnt vmcnt(6)
	v_lshlrev_b32_e32 v28, 16, v68
	v_and_b32_e32 v29, 0xffff0000, v68
	v_lshlrev_b32_e32 v26, 16, v69
	v_and_b32_e32 v27, 0xffff0000, v69
	v_lshlrev_b32_e32 v68, 16, v70
	v_and_b32_e32 v69, 0xffff0000, v70
	v_lshlrev_b32_e32 v30, 16, v71
	v_and_b32_e32 v31, 0xffff0000, v71
	s_waitcnt lgkmcnt(0)
	v_sub_f32_e32 v29, v29, v24
	v_sub_f32_e32 v28, v28, v24
	v_sub_f32_e32 v27, v27, v24
	v_sub_f32_e32 v26, v26, v24
	v_pk_mul_f32 v[28:29], v[24:25], v[28:29] op_sel:[1,0]
	v_sub_f32_e32 v31, v31, v24
	v_sub_f32_e32 v30, v30, v24
	v_sub_f32_e32 v69, v69, v24
	v_sub_f32_e32 v68, v68, v24
	v_pk_mul_f32 v[26:27], v[24:25], v[26:27] op_sel:[1,0]
	s_waitcnt vmcnt(5)
	v_pk_fma_f32 v[28:29], v[52:53], v[28:29], v[60:61]
	v_pk_mul_f32 v[68:69], v[24:25], v[68:69] op_sel:[1,0]
	v_pk_mul_f32 v[24:25], v[24:25], v[30:31] op_sel:[1,0]
	v_pk_fma_f32 v[26:27], v[54:55], v[26:27], v[62:63]
	v_pk_fma_f32 v[24:25], v[38:39], v[24:25], v[50:51]
	v_cvt_pk_bf16_f32 v28, v28, v29
	v_pk_fma_f32 v[30:31], v[36:37], v[68:69], v[48:49]
	v_cvt_pk_bf16_f32 v26, v26, v27
	v_and_b32_e32 v29, 0xffff0000, v64
	v_cvt_pk_bf16_f32 v27, v30, v31
	v_cvt_pk_bf16_f32 v24, v24, v25
	ds_write_b16 v186, v28
	ds_write_b16_d16_hi v186, v28 offset:272
	ds_write_b16 v186, v26 offset:544
	ds_write_b16_d16_hi v186, v26 offset:816
	ds_write_b16 v186, v27 offset:1088
	ds_write_b16_d16_hi v186, v27 offset:1360
	ds_write_b16 v186, v24 offset:1632
	ds_write_b16_d16_hi v186, v24 offset:1904
	ds_read_b64 v[24:25], v187
	v_lshlrev_b32_e32 v28, 16, v64
	v_lshlrev_b32_e32 v26, 16, v65
	v_and_b32_e32 v27, 0xffff0000, v65
	v_lshlrev_b32_e32 v64, 16, v66
	v_and_b32_e32 v65, 0xffff0000, v66
	v_lshlrev_b32_e32 v30, 16, v67
	v_and_b32_e32 v31, 0xffff0000, v67
	s_waitcnt lgkmcnt(0)
	v_sub_f32_e32 v29, v29, v24
	v_sub_f32_e32 v28, v28, v24
	v_sub_f32_e32 v27, v27, v24
	v_sub_f32_e32 v26, v26, v24
	v_pk_mul_f32 v[28:29], v[24:25], v[28:29] op_sel:[1,0]
	v_sub_f32_e32 v31, v31, v24
	v_sub_f32_e32 v30, v30, v24
	v_sub_f32_e32 v65, v65, v24
	v_sub_f32_e32 v64, v64, v24
	v_pk_mul_f32 v[26:27], v[24:25], v[26:27] op_sel:[1,0]
	v_pk_fma_f32 v[28:29], v[52:53], v[28:29], v[60:61]
	v_pk_mul_f32 v[64:65], v[24:25], v[64:65] op_sel:[1,0]
	v_pk_mul_f32 v[24:25], v[24:25], v[30:31] op_sel:[1,0]
	v_pk_fma_f32 v[26:27], v[54:55], v[26:27], v[62:63]
	v_pk_fma_f32 v[24:25], v[38:39], v[24:25], v[50:51]
	v_cvt_pk_bf16_f32 v28, v28, v29
	s_and_b64 vcc, exec, s[4:5]
	v_pk_fma_f32 v[30:31], v[36:37], v[64:65], v[48:49]
	v_cvt_pk_bf16_f32 v26, v26, v27
	s_nop 0
	v_cvt_pk_bf16_f32 v27, v30, v31
	v_cvt_pk_bf16_f32 v24, v24, v25
	ds_write_b16 v188, v28
	ds_write_b16_d16_hi v188, v28 offset:272
	ds_write_b16 v188, v26 offset:544
	ds_write_b16_d16_hi v188, v26 offset:816
	ds_write_b16 v188, v27 offset:1088
	ds_write_b16_d16_hi v188, v27 offset:1360
	ds_write_b16 v188, v24 offset:1632
	ds_write_b16_d16_hi v188, v24 offset:1904
	s_cbranch_vccnz .LBB0_699
	ds_read_b64 v[24:25], v189
	v_lshlrev_b32_e32 v28, 16, v0
	v_and_b32_e32 v29, 0xffff0000, v0
	v_lshlrev_b32_e32 v26, 16, v1
	v_and_b32_e32 v27, 0xffff0000, v1
	v_lshlrev_b32_e32 v64, 16, v2
	v_and_b32_e32 v65, 0xffff0000, v2
	v_lshlrev_b32_e32 v30, 16, v3
	v_and_b32_e32 v31, 0xffff0000, v3
	s_waitcnt lgkmcnt(0)
	v_sub_f32_e32 v29, v29, v24
	v_sub_f32_e32 v28, v28, v24
	v_sub_f32_e32 v27, v27, v24
	v_sub_f32_e32 v26, v26, v24
	v_pk_mul_f32 v[28:29], v[24:25], v[28:29] op_sel:[1,0]
	v_sub_f32_e32 v31, v31, v24
	v_sub_f32_e32 v30, v30, v24
	v_sub_f32_e32 v65, v65, v24
	v_sub_f32_e32 v64, v64, v24
	v_pk_mul_f32 v[26:27], v[24:25], v[26:27] op_sel:[1,0]
	v_pk_fma_f32 v[28:29], v[52:53], v[28:29], v[60:61]
	v_pk_mul_f32 v[64:65], v[24:25], v[64:65] op_sel:[1,0]
	v_pk_mul_f32 v[24:25], v[24:25], v[30:31] op_sel:[1,0]
	v_pk_fma_f32 v[26:27], v[54:55], v[26:27], v[62:63]
	v_pk_fma_f32 v[24:25], v[38:39], v[24:25], v[50:51]
	v_cvt_pk_bf16_f32 v28, v28, v29
	v_pk_fma_f32 v[30:31], v[36:37], v[64:65], v[48:49]
	v_cvt_pk_bf16_f32 v26, v26, v27
	v_and_b32_e32 v29, 0xffff0000, v4
	v_cvt_pk_bf16_f32 v27, v30, v31
	v_cvt_pk_bf16_f32 v24, v24, v25
	ds_write_b16 v190, v28
	ds_write_b16_d16_hi v190, v28 offset:272
	ds_write_b16 v190, v26 offset:544
	ds_write_b16_d16_hi v190, v26 offset:816
	ds_write_b16 v190, v27 offset:1088
	ds_write_b16_d16_hi v190, v27 offset:1360
	ds_write_b16 v190, v24 offset:1632
	ds_write_b16_d16_hi v190, v24 offset:1904
	ds_read_b64 v[24:25], v191
	v_lshlrev_b32_e32 v28, 16, v4
	v_lshlrev_b32_e32 v26, 16, v5
	v_and_b32_e32 v27, 0xffff0000, v5
	v_lshlrev_b32_e32 v64, 16, v6
	s_waitcnt lgkmcnt(0)
	v_sub_f32_e32 v29, v29, v24
	v_sub_f32_e32 v28, v28, v24
	v_and_b32_e32 v65, 0xffff0000, v6
	v_lshlrev_b32_e32 v30, 16, v7
	v_and_b32_e32 v31, 0xffff0000, v7
	v_pk_mul_f32 v[28:29], v[24:25], v[28:29] op_sel:[1,0]
	v_sub_f32_e32 v27, v27, v24
	v_sub_f32_e32 v26, v26, v24
	v_pk_fma_f32 v[28:29], v[52:53], v[28:29], v[60:61]
	v_sub_f32_e32 v31, v31, v24
	v_sub_f32_e32 v30, v30, v24
	v_sub_f32_e32 v53, v65, v24
	v_sub_f32_e32 v52, v64, v24
	v_pk_mul_f32 v[26:27], v[24:25], v[26:27] op_sel:[1,0]
	v_pk_mul_f32 v[52:53], v[24:25], v[52:53] op_sel:[1,0]
	v_pk_mul_f32 v[24:25], v[24:25], v[30:31] op_sel:[1,0]
	v_pk_fma_f32 v[26:27], v[54:55], v[26:27], v[62:63]
	v_pk_fma_f32 v[24:25], v[38:39], v[24:25], v[50:51]
	v_cvt_pk_bf16_f32 v28, v28, v29
	v_pk_fma_f32 v[30:31], v[36:37], v[52:53], v[48:49]
	v_cvt_pk_bf16_f32 v26, v26, v27
	s_nop 0
	v_cvt_pk_bf16_f32 v27, v30, v31
	v_cvt_pk_bf16_f32 v24, v24, v25
	ds_write_b16 v192, v28
	ds_write_b16_d16_hi v192, v28 offset:272
	ds_write_b16 v192, v26 offset:544
	ds_write_b16_d16_hi v192, v26 offset:816
	ds_write_b16 v192, v27 offset:1088
	ds_write_b16_d16_hi v192, v27 offset:1360
	ds_write_b16 v192, v24 offset:1632
	ds_write_b16_d16_hi v192, v24 offset:1904

.LBB0_703:
	s_nop 0
	ds_read_b128 v[60:63], v248 offset:1552
	ds_read_b128 v[72:75], v248 offset:1536
	ds_read_b128 v[68:71], v248 offset:5648
	ds_read_b128 v[76:79], v248 offset:5632
	v_add_co_u32_e32 v24, vcc, 0x18000, v148
	s_waitcnt vmcnt(5)
	v_mov_b64_e32 v[54:55], v[46:47]
	v_addc_co_u32_e32 v25, vcc, 0, v149, vcc
	global_load_dwordx4 v[64:67], v[24:25], off
	global_load_dwordx4 v[48:51], v[24:25], off offset:64
	s_and_b64 vcc, exec, s[4:5]
	v_mov_b64_e32 v[52:53], v[44:45]
	s_cbranch_vccnz .LBB0_705
	v_add_co_u32_e32 v24, vcc, 0x18000, v148
	s_nop 1
	v_addc_co_u32_e32 v25, vcc, 0, v149, vcc
	global_load_dwordx4 v[52:55], v[24:25], off offset:128

; #define LAS __attribute__((address_space(3)))
; __device__ __forceinline__ unsigned cvt_pk_bf16(float lo, float hi) { unsigned r; asm volatile("v_cvt_pk_bf16_f32 %0, %1, %2" : "=v"(r) : "v"(lo), "v"(hi)); return r; }
; __device__ __forceinline__ float bf_lo(unsigned u) { return __uint_as_float(u << 16); }
; __device__ __forceinline__ float bf_hi(unsigned u) { return __uint_as_float(u & 0xffff0000u); }
; __global__ void __launch_bounds__(NTHR, 2) fwd_megakernel(Args args) {
;     ...
;                 for (int k = 0; k < 4; ++k) if (k < nk) { const int j = jb + 32 * k; const u32x4 v = pv[k]; const f32x2 ms = st[j];
;                     const f32x4 x0 = (f32x4){bf_lo(v.x), bf_hi(v.x), bf_lo(v.y), bf_hi(v.y)}, x1 = (f32x4){bf_lo(v.z), bf_hi(v.z), bf_lo(v.w), bf_hi(v.w)};
;                     const f32x4 y0 = (x0 - ms.x) * ms.y * pg0 + pb0, y1 = (x1 - ms.x) * ms.y * pg1 + pb1;
;                     LAS bf16_t* d = Bc + (c8 * 8) * LDB + (j ^ (8 * c8));
;                     const unsigned p0 = cvt_pk_bf16(y0[0], y0[1]), p1 = cvt_pk_bf16(y0[2], y0[3]), p2 = cvt_pk_bf16(y1[0], y1[1]), p3 = cvt_pk_bf16(y1[2], y1[3]);
;                     d[0 * LDB] = (bf16_t)(p0 & 0xffffu); d[1 * LDB] = (bf16_t)(p0 >> 16); d[2 * LDB] = (bf16_t)(p1 & 0xffffu); d[3 * LDB] = (bf16_t)(p1 >> 16);
;                     d[4 * LDB] = (bf16_t)(p2 & 0xffffu); d[5 * LDB] = (bf16_t)(p2 >> 16); d[6 * LDB] = (bf16_t)(p3 & 0xffffu); d[7 * LDB] = (bf16_t)(p3 >> 16); }
.LBB0_711:
	ds_read_b64 v[32:33], v181
	s_waitcnt vmcnt(6)
	v_lshlrev_b32_e32 v40, 16, v84
	v_and_b32_e32 v41, 0xffff0000, v84
	v_lshlrev_b32_e32 v34, 16, v85
	v_and_b32_e32 v35, 0xffff0000, v85
	v_lshlrev_b32_e32 v44, 16, v86
	v_and_b32_e32 v45, 0xffff0000, v86
	v_lshlrev_b32_e32 v42, 16, v87
	v_and_b32_e32 v43, 0xffff0000, v87
	s_waitcnt lgkmcnt(0)
	v_sub_f32_e32 v41, v41, v32
	v_sub_f32_e32 v40, v40, v32
	v_sub_f32_e32 v35, v35, v32
	v_sub_f32_e32 v34, v34, v32
	v_pk_mul_f32 v[40:41], v[32:33], v[40:41] op_sel:[1,0]
	v_sub_f32_e32 v43, v43, v32
	v_sub_f32_e32 v42, v42, v32
	v_sub_f32_e32 v45, v45, v32
	v_sub_f32_e32 v44, v44, v32
	v_pk_mul_f32 v[34:35], v[32:33], v[34:35] op_sel:[1,0]
	s_waitcnt vmcnt(5)
	v_pk_fma_f32 v[40:41], v[72:73], v[40:41], v[76:77]
	v_pk_mul_f32 v[44:45], v[32:33], v[44:45] op_sel:[1,0]
	v_pk_mul_f32 v[32:33], v[32:33], v[42:43] op_sel:[1,0]
	v_pk_fma_f32 v[34:35], v[74:75], v[34:35], v[78:79]
	v_pk_fma_f32 v[32:33], v[62:63], v[32:33], v[70:71]
	v_cvt_pk_bf16_f32 v40, v40, v41
	v_pk_fma_f32 v[42:43], v[60:61], v[44:45], v[68:69]
	v_cvt_pk_bf16_f32 v34, v34, v35
	v_and_b32_e32 v41, 0xffff0000, v80
	v_cvt_pk_bf16_f32 v35, v42, v43
	v_cvt_pk_bf16_f32 v32, v32, v33
	ds_write_b16 v186, v40 offset:34816
	ds_write_b16_d16_hi v186, v40 offset:35088
	ds_write_b16 v186, v34 offset:35360
	ds_write_b16_d16_hi v186, v34 offset:35632
	ds_write_b16 v186, v35 offset:35904
	ds_write_b16_d16_hi v186, v35 offset:36176
	ds_write_b16 v186, v32 offset:36448
	ds_write_b16_d16_hi v186, v32 offset:36720
	ds_read_b64 v[32:33], v187
	v_lshlrev_b32_e32 v40, 16, v80
	v_lshlrev_b32_e32 v34, 16, v81
	v_and_b32_e32 v35, 0xffff0000, v81
	v_lshlrev_b32_e32 v44, 16, v82
	v_and_b32_e32 v45, 0xffff0000, v82
	v_lshlrev_b32_e32 v42, 16, v83
	v_and_b32_e32 v43, 0xffff0000, v83
	s_waitcnt lgkmcnt(0)
	v_sub_f32_e32 v41, v41, v32
	v_sub_f32_e32 v40, v40, v32
	v_sub_f32_e32 v35, v35, v32
	v_sub_f32_e32 v34, v34, v32
	v_pk_mul_f32 v[40:41], v[32:33], v[40:41] op_sel:[1,0]
	v_sub_f32_e32 v43, v43, v32
	v_sub_f32_e32 v42, v42, v32
	v_sub_f32_e32 v45, v45, v32
	v_sub_f32_e32 v44, v44, v32
	v_pk_mul_f32 v[34:35], v[32:33], v[34:35] op_sel:[1,0]
	v_pk_fma_f32 v[40:41], v[72:73], v[40:41], v[76:77]
	v_pk_mul_f32 v[44:45], v[32:33], v[44:45] op_sel:[1,0]
	v_pk_mul_f32 v[32:33], v[32:33], v[42:43] op_sel:[1,0]
	v_pk_fma_f32 v[34:35], v[74:75], v[34:35], v[78:79]
	v_pk_fma_f32 v[32:33], v[62:63], v[32:33], v[70:71]
	v_cvt_pk_bf16_f32 v40, v40, v41
	s_and_b64 vcc, exec, s[4:5]
	v_pk_fma_f32 v[42:43], v[60:61], v[44:45], v[68:69]
	v_cvt_pk_bf16_f32 v34, v34, v35
	s_nop 0
	v_cvt_pk_bf16_f32 v35, v42, v43
	v_cvt_pk_bf16_f32 v32, v32, v33
	ds_write_b16 v188, v40 offset:34816
	ds_write_b16_d16_hi v188, v40 offset:35088
	ds_write_b16 v188, v34 offset:35360
	ds_write_b16_d16_hi v188, v34 offset:35632
	ds_write_b16 v188, v35 offset:35904
	ds_write_b16_d16_hi v188, v35 offset:36176
	ds_write_b16 v188, v32 offset:36448
	ds_write_b16_d16_hi v188, v32 offset:36720
	s_cbranch_vccnz .LBB0_713
	ds_read_b64 v[32:33], v189
	v_lshlrev_b32_e32 v40, 16, v0
	v_and_b32_e32 v41, 0xffff0000, v0
	v_lshlrev_b32_e32 v34, 16, v1
	v_and_b32_e32 v35, 0xffff0000, v1
	v_lshlrev_b32_e32 v44, 16, v2
	v_and_b32_e32 v45, 0xffff0000, v2
	v_lshlrev_b32_e32 v42, 16, v3
	v_and_b32_e32 v43, 0xffff0000, v3
	s_waitcnt lgkmcnt(0)
	v_sub_f32_e32 v41, v41, v32
	v_sub_f32_e32 v40, v40, v32
	v_sub_f32_e32 v35, v35, v32
	v_sub_f32_e32 v34, v34, v32
	v_pk_mul_f32 v[40:41], v[32:33], v[40:41] op_sel:[1,0]
	v_sub_f32_e32 v43, v43, v32
	v_sub_f32_e32 v42, v42, v32
	v_sub_f32_e32 v45, v45, v32
	v_sub_f32_e32 v44, v44, v32
	v_pk_mul_f32 v[34:35], v[32:33], v[34:35] op_sel:[1,0]
	v_pk_fma_f32 v[40:41], v[72:73], v[40:41], v[76:77]
	v_pk_mul_f32 v[44:45], v[32:33], v[44:45] op_sel:[1,0]
	v_pk_mul_f32 v[32:33], v[32:33], v[42:43] op_sel:[1,0]
	v_pk_fma_f32 v[34:35], v[74:75], v[34:35], v[78:79]
	v_pk_fma_f32 v[32:33], v[62:63], v[32:33], v[70:71]
	v_cvt_pk_bf16_f32 v40, v40, v41
	v_pk_fma_f32 v[42:43], v[60:61], v[44:45], v[68:69]
	v_cvt_pk_bf16_f32 v34, v34, v35
	v_and_b32_e32 v41, 0xffff0000, v4
	v_cvt_pk_bf16_f32 v35, v42, v43
	v_cvt_pk_bf16_f32 v32, v32, v33
	ds_write_b16 v190, v40 offset:34816
	ds_write_b16_d16_hi v190, v40 offset:35088
	ds_write_b16 v190, v34 offset:35360
	ds_write_b16_d16_hi v190, v34 offset:35632
	ds_write_b16 v190, v35 offset:35904
	ds_write_b16_d16_hi v190, v35 offset:36176
	ds_write_b16 v190, v32 offset:36448
	ds_write_b16_d16_hi v190, v32 offset:36720
	ds_read_b64 v[32:33], v191
	v_lshlrev_b32_e32 v40, 16, v4
	v_lshlrev_b32_e32 v34, 16, v5
	v_and_b32_e32 v35, 0xffff0000, v5
	v_lshlrev_b32_e32 v44, 16, v6
	v_and_b32_e32 v45, 0xffff0000, v6
	v_lshlrev_b32_e32 v42, 16, v7
	v_and_b32_e32 v43, 0xffff0000, v7
	s_waitcnt lgkmcnt(0)
	v_sub_f32_e32 v41, v41, v32
	v_sub_f32_e32 v40, v40, v32
	v_sub_f32_e32 v35, v35, v32
	v_sub_f32_e32 v34, v34, v32
	v_pk_mul_f32 v[40:41], v[32:33], v[40:41] op_sel:[1,0]
	v_sub_f32_e32 v43, v43, v32
	v_sub_f32_e32 v42, v42, v32
	v_sub_f32_e32 v45, v45, v32
	v_sub_f32_e32 v44, v44, v32
	v_pk_mul_f32 v[34:35], v[32:33], v[34:35] op_sel:[1,0]
	v_pk_fma_f32 v[40:41], v[72:73], v[40:41], v[76:77]
	v_pk_mul_f32 v[44:45], v[32:33], v[44:45] op_sel:[1,0]
	v_pk_mul_f32 v[32:33], v[32:33], v[42:43] op_sel:[1,0]
	v_pk_fma_f32 v[34:35], v[74:75], v[34:35], v[78:79]
	v_pk_fma_f32 v[32:33], v[62:63], v[32:33], v[70:71]
	v_cvt_pk_bf16_f32 v40, v40, v41
	v_pk_fma_f32 v[42:43], v[60:61], v[44:45], v[68:69]
	v_cvt_pk_bf16_f32 v34, v34, v35
	s_nop 0
	v_cvt_pk_bf16_f32 v35, v42, v43
	v_cvt_pk_bf16_f32 v32, v32, v33
	ds_write_b16 v192, v40 offset:34816
	ds_write_b16_d16_hi v192, v40 offset:35088
	ds_write_b16 v192, v34 offset:35360
	ds_write_b16_d16_hi v192, v34 offset:35632
	ds_write_b16 v192, v35 offset:35904
	ds_write_b16_d16_hi v192, v35 offset:36176
	ds_write_b16 v192, v32 offset:36448
	ds_write_b16_d16_hi v192, v32 offset:36720

.LBB0_717:
	s_nop 0
	ds_read_b128 v[68:71], v248 offset:2064
	ds_read_b128 v[80:83], v248 offset:2048
	ds_read_b128 v[76:79], v248 offset:6160
	ds_read_b128 v[84:87], v248 offset:6144
	v_add_co_u32_e32 v32, vcc, 0x20000, v148
	s_waitcnt vmcnt(5)
	v_mov_b64_e32 v[62:63], v[54:55]
	v_addc_co_u32_e32 v33, vcc, 0, v149, vcc
	global_load_dwordx4 v[72:75], v[32:33], off
	global_load_dwordx4 v[56:59], v[32:33], off offset:64
	s_and_b64 vcc, exec, s[4:5]
	v_mov_b64_e32 v[60:61], v[52:53]
	s_cbranch_vccnz .LBB0_719
	v_add_co_u32_e32 v32, vcc, 0x20000, v148
	s_nop 1
	v_addc_co_u32_e32 v33, vcc, 0, v149, vcc
	global_load_dwordx4 v[60:63], v[32:33], off offset:128

; #define LAS __attribute__((address_space(3)))
; __device__ __forceinline__ unsigned cvt_pk_bf16(float lo, float hi) { unsigned r; asm volatile("v_cvt_pk_bf16_f32 %0, %1, %2" : "=v"(r) : "v"(lo), "v"(hi)); return r; }
; __device__ __forceinline__ float bf_lo(unsigned u) { return __uint_as_float(u << 16); }
; __device__ __forceinline__ float bf_hi(unsigned u) { return __uint_as_float(u & 0xffff0000u); }
; __global__ void __launch_bounds__(NTHR, 2) fwd_megakernel(Args args) {
;     ...
;                 for (int k = 0; k < 4; ++k) if (k < nk) { const int j = jb + 32 * k; const u32x4 v = pv[k]; const f32x2 ms = st[j];
;                     const f32x4 x0 = (f32x4){bf_lo(v.x), bf_hi(v.x), bf_lo(v.y), bf_hi(v.y)}, x1 = (f32x4){bf_lo(v.z), bf_hi(v.z), bf_lo(v.w), bf_hi(v.w)};
;                     const f32x4 y0 = (x0 - ms.x) * ms.y * pg0 + pb0, y1 = (x1 - ms.x) * ms.y * pg1 + pb1;
;                     LAS bf16_t* d = Bc + (c8 * 8) * LDB + (j ^ (8 * c8));
;                     const unsigned p0 = cvt_pk_bf16(y0[0], y0[1]), p1 = cvt_pk_bf16(y0[2], y0[3]), p2 = cvt_pk_bf16(y1[0], y1[1]), p3 = cvt_pk_bf16(y1[2], y1[3]);
;                     d[0 * LDB] = (bf16_t)(p0 & 0xffffu); d[1 * LDB] = (bf16_t)(p0 >> 16); d[2 * LDB] = (bf16_t)(p1 & 0xffffu); d[3 * LDB] = (bf16_t)(p1 >> 16);
;                     d[4 * LDB] = (bf16_t)(p2 & 0xffffu); d[5 * LDB] = (bf16_t)(p2 >> 16); d[6 * LDB] = (bf16_t)(p3 & 0xffffu); d[7 * LDB] = (bf16_t)(p3 >> 16); }
.LBB0_725:
	ds_read_b64 v[36:37], v181
	s_waitcnt vmcnt(6)
	v_lshlrev_b32_e32 v48, 16, v92
	v_and_b32_e32 v49, 0xffff0000, v92
	v_lshlrev_b32_e32 v38, 16, v93
	v_and_b32_e32 v39, 0xffff0000, v93
	v_lshlrev_b32_e32 v52, 16, v94
	v_and_b32_e32 v53, 0xffff0000, v94
	v_lshlrev_b32_e32 v50, 16, v95
	v_and_b32_e32 v51, 0xffff0000, v95
	s_waitcnt lgkmcnt(0)
	v_sub_f32_e32 v49, v49, v36
	v_sub_f32_e32 v48, v48, v36
	v_sub_f32_e32 v39, v39, v36
	v_sub_f32_e32 v38, v38, v36
	v_pk_mul_f32 v[48:49], v[36:37], v[48:49] op_sel:[1,0]
	v_sub_f32_e32 v51, v51, v36
	v_sub_f32_e32 v50, v50, v36
	v_sub_f32_e32 v53, v53, v36
	v_sub_f32_e32 v52, v52, v36
	v_pk_mul_f32 v[38:39], v[36:37], v[38:39] op_sel:[1,0]
	s_waitcnt vmcnt(5)
	v_pk_fma_f32 v[48:49], v[80:81], v[48:49], v[84:85]
	v_pk_mul_f32 v[52:53], v[36:37], v[52:53] op_sel:[1,0]
	v_pk_mul_f32 v[36:37], v[36:37], v[50:51] op_sel:[1,0]
	v_pk_fma_f32 v[38:39], v[82:83], v[38:39], v[86:87]
	v_pk_fma_f32 v[36:37], v[70:71], v[36:37], v[78:79]
	v_cvt_pk_bf16_f32 v48, v48, v49
	v_pk_fma_f32 v[50:51], v[68:69], v[52:53], v[76:77]
	v_cvt_pk_bf16_f32 v38, v38, v39
	v_and_b32_e32 v49, 0xffff0000, v88
	v_cvt_pk_bf16_f32 v39, v50, v51
	v_cvt_pk_bf16_f32 v36, v36, v37
	ds_write_b16 v186, v48
	ds_write_b16_d16_hi v186, v48 offset:272
	ds_write_b16 v186, v38 offset:544
	ds_write_b16_d16_hi v186, v38 offset:816
	ds_write_b16 v186, v39 offset:1088
	ds_write_b16_d16_hi v186, v39 offset:1360
	ds_write_b16 v186, v36 offset:1632
	ds_write_b16_d16_hi v186, v36 offset:1904
	ds_read_b64 v[36:37], v187
	v_lshlrev_b32_e32 v48, 16, v88
	v_lshlrev_b32_e32 v38, 16, v89
	v_and_b32_e32 v39, 0xffff0000, v89
	v_lshlrev_b32_e32 v52, 16, v90
	v_and_b32_e32 v53, 0xffff0000, v90
	v_lshlrev_b32_e32 v50, 16, v91
	v_and_b32_e32 v51, 0xffff0000, v91
	s_waitcnt lgkmcnt(0)
	v_sub_f32_e32 v49, v49, v36
	v_sub_f32_e32 v48, v48, v36
	v_sub_f32_e32 v39, v39, v36
	v_sub_f32_e32 v38, v38, v36
	v_pk_mul_f32 v[48:49], v[36:37], v[48:49] op_sel:[1,0]
	v_sub_f32_e32 v51, v51, v36
	v_sub_f32_e32 v50, v50, v36
	v_sub_f32_e32 v53, v53, v36
	v_sub_f32_e32 v52, v52, v36
	v_pk_mul_f32 v[38:39], v[36:37], v[38:39] op_sel:[1,0]
	v_pk_fma_f32 v[48:49], v[80:81], v[48:49], v[84:85]
	v_pk_mul_f32 v[52:53], v[36:37], v[52:53] op_sel:[1,0]
	v_pk_mul_f32 v[36:37], v[36:37], v[50:51] op_sel:[1,0]
	v_pk_fma_f32 v[38:39], v[82:83], v[38:39], v[86:87]
	v_pk_fma_f32 v[36:37], v[70:71], v[36:37], v[78:79]
	v_cvt_pk_bf16_f32 v48, v48, v49
	s_and_b64 vcc, exec, s[4:5]
	v_pk_fma_f32 v[50:51], v[68:69], v[52:53], v[76:77]
	v_cvt_pk_bf16_f32 v38, v38, v39
	s_nop 0
	v_cvt_pk_bf16_f32 v39, v50, v51
	v_cvt_pk_bf16_f32 v36, v36, v37
	ds_write_b16 v188, v48
	ds_write_b16_d16_hi v188, v48 offset:272
	ds_write_b16 v188, v38 offset:544
	ds_write_b16_d16_hi v188, v38 offset:816
	ds_write_b16 v188, v39 offset:1088
	ds_write_b16_d16_hi v188, v39 offset:1360
	ds_write_b16 v188, v36 offset:1632
	ds_write_b16_d16_hi v188, v36 offset:1904
	s_cbranch_vccnz .LBB0_727
	ds_read_b64 v[36:37], v189
	v_lshlrev_b32_e32 v48, 16, v0
	v_and_b32_e32 v49, 0xffff0000, v0
	v_lshlrev_b32_e32 v38, 16, v1
	v_and_b32_e32 v39, 0xffff0000, v1
	v_lshlrev_b32_e32 v52, 16, v2
	v_and_b32_e32 v53, 0xffff0000, v2
	v_lshlrev_b32_e32 v50, 16, v3
	v_and_b32_e32 v51, 0xffff0000, v3
	s_waitcnt lgkmcnt(0)
	v_sub_f32_e32 v49, v49, v36
	v_sub_f32_e32 v48, v48, v36
	v_sub_f32_e32 v39, v39, v36
	v_sub_f32_e32 v38, v38, v36
	v_pk_mul_f32 v[48:49], v[36:37], v[48:49] op_sel:[1,0]
	v_sub_f32_e32 v51, v51, v36
	v_sub_f32_e32 v50, v50, v36
	v_sub_f32_e32 v53, v53, v36
	v_sub_f32_e32 v52, v52, v36
	v_pk_mul_f32 v[38:39], v[36:37], v[38:39] op_sel:[1,0]
	v_pk_fma_f32 v[48:49], v[80:81], v[48:49], v[84:85]
	v_pk_mul_f32 v[52:53], v[36:37], v[52:53] op_sel:[1,0]
	v_pk_mul_f32 v[36:37], v[36:37], v[50:51] op_sel:[1,0]
	v_pk_fma_f32 v[38:39], v[82:83], v[38:39], v[86:87]
	v_pk_fma_f32 v[36:37], v[70:71], v[36:37], v[78:79]
	v_cvt_pk_bf16_f32 v48, v48, v49
	v_pk_fma_f32 v[50:51], v[68:69], v[52:53], v[76:77]
	v_cvt_pk_bf16_f32 v38, v38, v39
	v_and_b32_e32 v49, 0xffff0000, v4
	v_cvt_pk_bf16_f32 v39, v50, v51
	v_cvt_pk_bf16_f32 v36, v36, v37
	ds_write_b16 v190, v48
	ds_write_b16_d16_hi v190, v48 offset:272
	ds_write_b16 v190, v38 offset:544
	ds_write_b16_d16_hi v190, v38 offset:816
	ds_write_b16 v190, v39 offset:1088
	ds_write_b16_d16_hi v190, v39 offset:1360
	ds_write_b16 v190, v36 offset:1632
	ds_write_b16_d16_hi v190, v36 offset:1904
	ds_read_b64 v[36:37], v191
	v_lshlrev_b32_e32 v48, 16, v4
	v_lshlrev_b32_e32 v38, 16, v5
	v_and_b32_e32 v39, 0xffff0000, v5
	v_lshlrev_b32_e32 v52, 16, v6
	v_and_b32_e32 v53, 0xffff0000, v6
	v_lshlrev_b32_e32 v50, 16, v7
	v_and_b32_e32 v51, 0xffff0000, v7
	s_waitcnt lgkmcnt(0)
	v_sub_f32_e32 v49, v49, v36
	v_sub_f32_e32 v48, v48, v36
	v_sub_f32_e32 v39, v39, v36
	v_sub_f32_e32 v38, v38, v36
	v_pk_mul_f32 v[48:49], v[36:37], v[48:49] op_sel:[1,0]
	v_sub_f32_e32 v51, v51, v36
	v_sub_f32_e32 v50, v50, v36
	v_sub_f32_e32 v53, v53, v36
	v_sub_f32_e32 v52, v52, v36
	v_pk_mul_f32 v[38:39], v[36:37], v[38:39] op_sel:[1,0]
	v_pk_fma_f32 v[48:49], v[80:81], v[48:49], v[84:85]
	v_pk_mul_f32 v[52:53], v[36:37], v[52:53] op_sel:[1,0]
	v_pk_mul_f32 v[36:37], v[36:37], v[50:51] op_sel:[1,0]
	v_pk_fma_f32 v[38:39], v[82:83], v[38:39], v[86:87]
	v_pk_fma_f32 v[36:37], v[70:71], v[36:37], v[78:79]
	v_cvt_pk_bf16_f32 v48, v48, v49
	v_pk_fma_f32 v[50:51], v[68:69], v[52:53], v[76:77]
	v_cvt_pk_bf16_f32 v38, v38, v39
	s_nop 0
	v_cvt_pk_bf16_f32 v39, v50, v51
	v_cvt_pk_bf16_f32 v36, v36, v37
	ds_write_b16 v192, v48
	ds_write_b16_d16_hi v192, v48 offset:272
	ds_write_b16 v192, v38 offset:544
	ds_write_b16_d16_hi v192, v38 offset:816
	ds_write_b16 v192, v39 offset:1088
	ds_write_b16_d16_hi v192, v39 offset:1360
	ds_write_b16 v192, v36 offset:1632
	ds_write_b16_d16_hi v192, v36 offset:1904

.LBB0_731:
	s_nop 0
	ds_read_b128 v[76:79], v248 offset:2576
	ds_read_b128 v[88:91], v248 offset:2560
	ds_read_b128 v[80:83], v248 offset:6672
	ds_read_b128 v[92:95], v248 offset:6656
	v_add_co_u32_e32 v36, vcc, 0x28000, v148
	s_waitcnt vmcnt(5)
	v_mov_b64_e32 v[70:71], v[62:63]
	v_addc_co_u32_e32 v37, vcc, 0, v149, vcc
	global_load_dwordx4 v[84:87], v[36:37], off
	global_load_dwordx4 v[64:67], v[36:37], off offset:64
	s_and_b64 vcc, exec, s[4:5]
	v_mov_b64_e32 v[68:69], v[60:61]
	s_cbranch_vccnz .LBB0_733
	v_add_co_u32_e32 v36, vcc, 0x28000, v148
	s_nop 1
	v_addc_co_u32_e32 v37, vcc, 0, v149, vcc
	global_load_dwordx4 v[68:71], v[36:37], off offset:128

; #define LAS __attribute__((address_space(3)))
; __device__ __forceinline__ unsigned cvt_pk_bf16(float lo, float hi) { unsigned r; asm volatile("v_cvt_pk_bf16_f32 %0, %1, %2" : "=v"(r) : "v"(lo), "v"(hi)); return r; }
; __device__ __forceinline__ float bf_lo(unsigned u) { return __uint_as_float(u << 16); }
; __device__ __forceinline__ float bf_hi(unsigned u) { return __uint_as_float(u & 0xffff0000u); }
; __global__ void __launch_bounds__(NTHR, 2) fwd_megakernel(Args args) {
;     ...
;                 for (int k = 0; k < 4; ++k) if (k < nk) { const int j = jb + 32 * k; const u32x4 v = pv[k]; const f32x2 ms = st[j];
;                     const f32x4 x0 = (f32x4){bf_lo(v.x), bf_hi(v.x), bf_lo(v.y), bf_hi(v.y)}, x1 = (f32x4){bf_lo(v.z), bf_hi(v.z), bf_lo(v.w), bf_hi(v.w)};
;                     const f32x4 y0 = (x0 - ms.x) * ms.y * pg0 + pb0, y1 = (x1 - ms.x) * ms.y * pg1 + pb1;
;                     LAS bf16_t* d = Bc + (c8 * 8) * LDB + (j ^ (8 * c8));
;                     const unsigned p0 = cvt_pk_bf16(y0[0], y0[1]), p1 = cvt_pk_bf16(y0[2], y0[3]), p2 = cvt_pk_bf16(y1[0], y1[1]), p3 = cvt_pk_bf16(y1[2], y1[3]);
;                     d[0 * LDB] = (bf16_t)(p0 & 0xffffu); d[1 * LDB] = (bf16_t)(p0 >> 16); d[2 * LDB] = (bf16_t)(p1 & 0xffffu); d[3 * LDB] = (bf16_t)(p1 >> 16);
;                     d[4 * LDB] = (bf16_t)(p2 & 0xffffu); d[5 * LDB] = (bf16_t)(p2 >> 16); d[6 * LDB] = (bf16_t)(p3 & 0xffffu); d[7 * LDB] = (bf16_t)(p3 >> 16); }
.LBB0_739:
	ds_read_b64 v[32:33], v181
	s_waitcnt vmcnt(6)
	v_lshlrev_b32_e32 v56, 16, v100
	v_and_b32_e32 v57, 0xffff0000, v100
	v_lshlrev_b32_e32 v34, 16, v101
	v_and_b32_e32 v35, 0xffff0000, v101
	v_lshlrev_b32_e32 v60, 16, v102
	v_and_b32_e32 v61, 0xffff0000, v102
	v_lshlrev_b32_e32 v58, 16, v103
	v_and_b32_e32 v59, 0xffff0000, v103
	s_waitcnt lgkmcnt(0)
	v_sub_f32_e32 v57, v57, v32
	v_sub_f32_e32 v56, v56, v32
	v_sub_f32_e32 v35, v35, v32
	v_sub_f32_e32 v34, v34, v32
	v_pk_mul_f32 v[56:57], v[32:33], v[56:57] op_sel:[1,0]
	v_sub_f32_e32 v59, v59, v32
	v_sub_f32_e32 v58, v58, v32
	v_sub_f32_e32 v61, v61, v32
	v_sub_f32_e32 v60, v60, v32
	v_pk_mul_f32 v[34:35], v[32:33], v[34:35] op_sel:[1,0]
	s_waitcnt vmcnt(5)
	v_pk_fma_f32 v[56:57], v[88:89], v[56:57], v[92:93]
	v_pk_mul_f32 v[60:61], v[32:33], v[60:61] op_sel:[1,0]
	v_pk_mul_f32 v[32:33], v[32:33], v[58:59] op_sel:[1,0]
	v_pk_fma_f32 v[34:35], v[90:91], v[34:35], v[94:95]
	v_pk_fma_f32 v[32:33], v[78:79], v[32:33], v[82:83]
	v_cvt_pk_bf16_f32 v56, v56, v57
	v_pk_fma_f32 v[58:59], v[76:77], v[60:61], v[80:81]
	v_cvt_pk_bf16_f32 v34, v34, v35
	v_and_b32_e32 v57, 0xffff0000, v96
	v_cvt_pk_bf16_f32 v35, v58, v59
	v_cvt_pk_bf16_f32 v32, v32, v33
	ds_write_b16 v186, v56 offset:34816
	ds_write_b16_d16_hi v186, v56 offset:35088
	ds_write_b16 v186, v34 offset:35360
	ds_write_b16_d16_hi v186, v34 offset:35632
	ds_write_b16 v186, v35 offset:35904
	ds_write_b16_d16_hi v186, v35 offset:36176
	ds_write_b16 v186, v32 offset:36448
	ds_write_b16_d16_hi v186, v32 offset:36720
	ds_read_b64 v[32:33], v187
	v_lshlrev_b32_e32 v56, 16, v96
	v_lshlrev_b32_e32 v34, 16, v97
	v_and_b32_e32 v35, 0xffff0000, v97
	v_lshlrev_b32_e32 v60, 16, v98
	v_and_b32_e32 v61, 0xffff0000, v98
	v_lshlrev_b32_e32 v58, 16, v99
	v_and_b32_e32 v59, 0xffff0000, v99
	s_waitcnt lgkmcnt(0)
	v_sub_f32_e32 v57, v57, v32
	v_sub_f32_e32 v56, v56, v32
	v_sub_f32_e32 v35, v35, v32
	v_sub_f32_e32 v34, v34, v32
	v_pk_mul_f32 v[56:57], v[32:33], v[56:57] op_sel:[1,0]
	v_sub_f32_e32 v59, v59, v32
	v_sub_f32_e32 v58, v58, v32
	v_sub_f32_e32 v61, v61, v32
	v_sub_f32_e32 v60, v60, v32
	v_pk_mul_f32 v[34:35], v[32:33], v[34:35] op_sel:[1,0]
	v_pk_fma_f32 v[56:57], v[88:89], v[56:57], v[92:93]
	v_pk_mul_f32 v[60:61], v[32:33], v[60:61] op_sel:[1,0]
	v_pk_mul_f32 v[32:33], v[32:33], v[58:59] op_sel:[1,0]
	v_pk_fma_f32 v[34:35], v[90:91], v[34:35], v[94:95]
	v_pk_fma_f32 v[32:33], v[78:79], v[32:33], v[82:83]
	v_cvt_pk_bf16_f32 v56, v56, v57
	s_and_b64 vcc, exec, s[4:5]
	v_pk_fma_f32 v[58:59], v[76:77], v[60:61], v[80:81]
	v_cvt_pk_bf16_f32 v34, v34, v35
	s_nop 0
	v_cvt_pk_bf16_f32 v35, v58, v59
	v_cvt_pk_bf16_f32 v32, v32, v33
	ds_write_b16 v188, v56 offset:34816
	ds_write_b16_d16_hi v188, v56 offset:35088
	ds_write_b16 v188, v34 offset:35360
	ds_write_b16_d16_hi v188, v34 offset:35632
	ds_write_b16 v188, v35 offset:35904
	ds_write_b16_d16_hi v188, v35 offset:36176
	ds_write_b16 v188, v32 offset:36448
	ds_write_b16_d16_hi v188, v32 offset:36720
	s_cbranch_vccnz .LBB0_741
	ds_read_b64 v[32:33], v189
	v_lshlrev_b32_e32 v56, 16, v0
	v_and_b32_e32 v57, 0xffff0000, v0
	v_lshlrev_b32_e32 v34, 16, v1
	v_and_b32_e32 v35, 0xffff0000, v1
	v_lshlrev_b32_e32 v60, 16, v2
	v_and_b32_e32 v61, 0xffff0000, v2
	v_lshlrev_b32_e32 v58, 16, v3
	v_and_b32_e32 v59, 0xffff0000, v3
	s_waitcnt lgkmcnt(0)
	v_sub_f32_e32 v57, v57, v32
	v_sub_f32_e32 v56, v56, v32
	v_sub_f32_e32 v35, v35, v32
	v_sub_f32_e32 v34, v34, v32
	v_pk_mul_f32 v[56:57], v[32:33], v[56:57] op_sel:[1,0]
	v_sub_f32_e32 v59, v59, v32
	v_sub_f32_e32 v58, v58, v32
	v_sub_f32_e32 v61, v61, v32
	v_sub_f32_e32 v60, v60, v32
	v_pk_mul_f32 v[34:35], v[32:33], v[34:35] op_sel:[1,0]
	v_pk_fma_f32 v[56:57], v[88:89], v[56:57], v[92:93]
	v_pk_mul_f32 v[60:61], v[32:33], v[60:61] op_sel:[1,0]
	v_pk_mul_f32 v[32:33], v[32:33], v[58:59] op_sel:[1,0]
	v_pk_fma_f32 v[34:35], v[90:91], v[34:35], v[94:95]
	v_pk_fma_f32 v[32:33], v[78:79], v[32:33], v[82:83]
	v_cvt_pk_bf16_f32 v56, v56, v57
	v_pk_fma_f32 v[58:59], v[76:77], v[60:61], v[80:81]
	v_cvt_pk_bf16_f32 v34, v34, v35
	v_and_b32_e32 v57, 0xffff0000, v4
	v_cvt_pk_bf16_f32 v35, v58, v59
	v_cvt_pk_bf16_f32 v32, v32, v33
	ds_write_b16 v190, v56 offset:34816
	ds_write_b16_d16_hi v190, v56 offset:35088
	ds_write_b16 v190, v34 offset:35360
	ds_write_b16_d16_hi v190, v34 offset:35632
	ds_write_b16 v190, v35 offset:35904
	ds_write_b16_d16_hi v190, v35 offset:36176
	ds_write_b16 v190, v32 offset:36448
	ds_write_b16_d16_hi v190, v32 offset:36720
	ds_read_b64 v[32:33], v191
	v_lshlrev_b32_e32 v56, 16, v4
	v_lshlrev_b32_e32 v34, 16, v5
	v_and_b32_e32 v35, 0xffff0000, v5
	v_lshlrev_b32_e32 v60, 16, v6
	v_and_b32_e32 v61, 0xffff0000, v6
	v_lshlrev_b32_e32 v58, 16, v7
	v_and_b32_e32 v59, 0xffff0000, v7
	s_waitcnt lgkmcnt(0)
	v_sub_f32_e32 v57, v57, v32
	v_sub_f32_e32 v56, v56, v32
	v_sub_f32_e32 v35, v35, v32
	v_sub_f32_e32 v34, v34, v32
	v_pk_mul_f32 v[56:57], v[32:33], v[56:57] op_sel:[1,0]
	v_sub_f32_e32 v59, v59, v32
	v_sub_f32_e32 v58, v58, v32
	v_sub_f32_e32 v61, v61, v32
	v_sub_f32_e32 v60, v60, v32
	v_pk_mul_f32 v[34:35], v[32:33], v[34:35] op_sel:[1,0]
	v_pk_fma_f32 v[56:57], v[88:89], v[56:57], v[92:93]
	v_pk_mul_f32 v[60:61], v[32:33], v[60:61] op_sel:[1,0]
	v_pk_mul_f32 v[32:33], v[32:33], v[58:59] op_sel:[1,0]
	v_pk_fma_f32 v[34:35], v[90:91], v[34:35], v[94:95]
	v_pk_fma_f32 v[32:33], v[78:79], v[32:33], v[82:83]
	v_cvt_pk_bf16_f32 v56, v56, v57
	v_pk_fma_f32 v[58:59], v[76:77], v[60:61], v[80:81]
	v_cvt_pk_bf16_f32 v34, v34, v35
	s_nop 0
	v_cvt_pk_bf16_f32 v35, v58, v59
	v_cvt_pk_bf16_f32 v32, v32, v33
	ds_write_b16 v192, v56 offset:34816
	ds_write_b16_d16_hi v192, v56 offset:35088
	ds_write_b16 v192, v34 offset:35360
	ds_write_b16_d16_hi v192, v34 offset:35632
	ds_write_b16 v192, v35 offset:35904
	ds_write_b16_d16_hi v192, v35 offset:36176
	ds_write_b16 v192, v32 offset:36448
	ds_write_b16_d16_hi v192, v32 offset:36720

.LBB0_745:
	s_nop 0
	ds_read_b128 v[32:35], v248 offset:3088
	ds_read_b128 v[96:99], v248 offset:3072
	ds_read_b128 v[92:95], v248 offset:7184
	ds_read_b128 v[100:103], v248 offset:7168
	v_add_co_u32_e32 v56, vcc, 0x30000, v148
	s_waitcnt vmcnt(5)
	v_mov_b64_e32 v[82:83], v[70:71]
	v_addc_co_u32_e32 v57, vcc, 0, v149, vcc
	global_load_dwordx4 v[88:91], v[56:57], off
	global_load_dwordx4 v[76:79], v[56:57], off offset:64
	s_and_b64 vcc, exec, s[4:5]
	v_mov_b64_e32 v[80:81], v[68:69]
	s_cbranch_vccnz .LBB0_747
	v_add_co_u32_e32 v56, vcc, 0x30000, v148
	s_nop 1
	v_addc_co_u32_e32 v57, vcc, 0, v149, vcc
	global_load_dwordx4 v[80:83], v[56:57], off offset:128

; #define LAS __attribute__((address_space(3)))
; __device__ __forceinline__ unsigned cvt_pk_bf16(float lo, float hi) { unsigned r; asm volatile("v_cvt_pk_bf16_f32 %0, %1, %2" : "=v"(r) : "v"(lo), "v"(hi)); return r; }
; __device__ __forceinline__ float bf_lo(unsigned u) { return __uint_as_float(u << 16); }
; __device__ __forceinline__ float bf_hi(unsigned u) { return __uint_as_float(u & 0xffff0000u); }
; __global__ void __launch_bounds__(NTHR, 2) fwd_megakernel(Args args) {
;     ...
;                 for (int k = 0; k < 4; ++k) if (k < nk) { const int j = jb + 32 * k; const u32x4 v = pv[k]; const f32x2 ms = st[j];
;                     const f32x4 x0 = (f32x4){bf_lo(v.x), bf_hi(v.x), bf_lo(v.y), bf_hi(v.y)}, x1 = (f32x4){bf_lo(v.z), bf_hi(v.z), bf_lo(v.w), bf_hi(v.w)};
;                     const f32x4 y0 = (x0 - ms.x) * ms.y * pg0 + pb0, y1 = (x1 - ms.x) * ms.y * pg1 + pb1;
;                     LAS bf16_t* d = Bc + (c8 * 8) * LDB + (j ^ (8 * c8));
;                     const unsigned p0 = cvt_pk_bf16(y0[0], y0[1]), p1 = cvt_pk_bf16(y0[2], y0[3]), p2 = cvt_pk_bf16(y1[0], y1[1]), p3 = cvt_pk_bf16(y1[2], y1[3]);
;                     d[0 * LDB] = (bf16_t)(p0 & 0xffffu); d[1 * LDB] = (bf16_t)(p0 >> 16); d[2 * LDB] = (bf16_t)(p1 & 0xffffu); d[3 * LDB] = (bf16_t)(p1 >> 16);
;                     d[4 * LDB] = (bf16_t)(p2 & 0xffffu); d[5 * LDB] = (bf16_t)(p2 >> 16); d[6 * LDB] = (bf16_t)(p3 & 0xffffu); d[7 * LDB] = (bf16_t)(p3 >> 16); }
.LBB0_753:
	ds_read_b64 v[36:37], v181
	s_waitcnt vmcnt(6)
	v_lshlrev_b32_e32 v64, 16, v108
	v_and_b32_e32 v65, 0xffff0000, v108
	v_lshlrev_b32_e32 v38, 16, v109
	v_and_b32_e32 v39, 0xffff0000, v109
	v_lshlrev_b32_e32 v68, 16, v110
	v_and_b32_e32 v69, 0xffff0000, v110
	v_lshlrev_b32_e32 v66, 16, v111
	v_and_b32_e32 v67, 0xffff0000, v111
	s_waitcnt lgkmcnt(0)
	v_sub_f32_e32 v65, v65, v36
	v_sub_f32_e32 v64, v64, v36
	v_sub_f32_e32 v39, v39, v36
	v_sub_f32_e32 v38, v38, v36
	v_pk_mul_f32 v[64:65], v[36:37], v[64:65] op_sel:[1,0]
	v_sub_f32_e32 v67, v67, v36
	v_sub_f32_e32 v66, v66, v36
	v_sub_f32_e32 v69, v69, v36
	v_sub_f32_e32 v68, v68, v36
	v_pk_mul_f32 v[38:39], v[36:37], v[38:39] op_sel:[1,0]
	s_waitcnt vmcnt(5)
	v_pk_fma_f32 v[64:65], v[96:97], v[64:65], v[100:101]
	v_pk_mul_f32 v[68:69], v[36:37], v[68:69] op_sel:[1,0]
	v_pk_mul_f32 v[36:37], v[36:37], v[66:67] op_sel:[1,0]
	v_pk_fma_f32 v[38:39], v[98:99], v[38:39], v[102:103]
	v_pk_fma_f32 v[36:37], v[34:35], v[36:37], v[94:95]
	v_cvt_pk_bf16_f32 v64, v64, v65
	v_pk_fma_f32 v[66:67], v[32:33], v[68:69], v[92:93]
	v_cvt_pk_bf16_f32 v38, v38, v39
	v_and_b32_e32 v65, 0xffff0000, v104
	v_cvt_pk_bf16_f32 v39, v66, v67
	v_cvt_pk_bf16_f32 v36, v36, v37
	ds_write_b16 v186, v64
	ds_write_b16_d16_hi v186, v64 offset:272
	ds_write_b16 v186, v38 offset:544
	ds_write_b16_d16_hi v186, v38 offset:816
	ds_write_b16 v186, v39 offset:1088
	ds_write_b16_d16_hi v186, v39 offset:1360
	ds_write_b16 v186, v36 offset:1632
	ds_write_b16_d16_hi v186, v36 offset:1904
	ds_read_b64 v[36:37], v187
	v_lshlrev_b32_e32 v64, 16, v104
	v_lshlrev_b32_e32 v38, 16, v105
	v_and_b32_e32 v39, 0xffff0000, v105
	v_lshlrev_b32_e32 v68, 16, v106
	v_and_b32_e32 v69, 0xffff0000, v106
	v_lshlrev_b32_e32 v66, 16, v107
	v_and_b32_e32 v67, 0xffff0000, v107
	s_waitcnt lgkmcnt(0)
	v_sub_f32_e32 v65, v65, v36
	v_sub_f32_e32 v64, v64, v36
	v_sub_f32_e32 v39, v39, v36
	v_sub_f32_e32 v38, v38, v36
	v_pk_mul_f32 v[64:65], v[36:37], v[64:65] op_sel:[1,0]
	v_sub_f32_e32 v67, v67, v36
	v_sub_f32_e32 v66, v66, v36
	v_sub_f32_e32 v69, v69, v36
	v_sub_f32_e32 v68, v68, v36
	v_pk_mul_f32 v[38:39], v[36:37], v[38:39] op_sel:[1,0]
	v_pk_fma_f32 v[64:65], v[96:97], v[64:65], v[100:101]
	v_pk_mul_f32 v[68:69], v[36:37], v[68:69] op_sel:[1,0]
	v_pk_mul_f32 v[36:37], v[36:37], v[66:67] op_sel:[1,0]
	v_pk_fma_f32 v[38:39], v[98:99], v[38:39], v[102:103]
	v_pk_fma_f32 v[36:37], v[34:35], v[36:37], v[94:95]
	v_cvt_pk_bf16_f32 v64, v64, v65
	s_and_b64 vcc, exec, s[4:5]
	v_pk_fma_f32 v[66:67], v[32:33], v[68:69], v[92:93]
	v_cvt_pk_bf16_f32 v38, v38, v39
	s_nop 0
	v_cvt_pk_bf16_f32 v39, v66, v67
	v_cvt_pk_bf16_f32 v36, v36, v37
	ds_write_b16 v188, v64
	ds_write_b16_d16_hi v188, v64 offset:272
	ds_write_b16 v188, v38 offset:544
	ds_write_b16_d16_hi v188, v38 offset:816
	ds_write_b16 v188, v39 offset:1088
	ds_write_b16_d16_hi v188, v39 offset:1360
	ds_write_b16 v188, v36 offset:1632
	ds_write_b16_d16_hi v188, v36 offset:1904
	s_cbranch_vccnz .LBB0_755
	ds_read_b64 v[36:37], v189
	v_lshlrev_b32_e32 v64, 16, v0
	v_and_b32_e32 v65, 0xffff0000, v0
	v_lshlrev_b32_e32 v38, 16, v1
	v_and_b32_e32 v39, 0xffff0000, v1
	v_lshlrev_b32_e32 v68, 16, v2
	v_and_b32_e32 v69, 0xffff0000, v2
	v_lshlrev_b32_e32 v66, 16, v3
	v_and_b32_e32 v67, 0xffff0000, v3
	s_waitcnt lgkmcnt(0)
	v_sub_f32_e32 v65, v65, v36
	v_sub_f32_e32 v64, v64, v36
	v_sub_f32_e32 v39, v39, v36
	v_sub_f32_e32 v38, v38, v36
	v_pk_mul_f32 v[64:65], v[36:37], v[64:65] op_sel:[1,0]
	v_sub_f32_e32 v67, v67, v36
	v_sub_f32_e32 v66, v66, v36
	v_sub_f32_e32 v69, v69, v36
	v_sub_f32_e32 v68, v68, v36
	v_pk_mul_f32 v[38:39], v[36:37], v[38:39] op_sel:[1,0]
	v_pk_fma_f32 v[64:65], v[96:97], v[64:65], v[100:101]
	v_pk_mul_f32 v[68:69], v[36:37], v[68:69] op_sel:[1,0]
	v_pk_mul_f32 v[36:37], v[36:37], v[66:67] op_sel:[1,0]
	v_pk_fma_f32 v[38:39], v[98:99], v[38:39], v[102:103]
	v_pk_fma_f32 v[36:37], v[34:35], v[36:37], v[94:95]
	v_cvt_pk_bf16_f32 v64, v64, v65
	v_pk_fma_f32 v[66:67], v[32:33], v[68:69], v[92:93]
	v_cvt_pk_bf16_f32 v38, v38, v39
	v_and_b32_e32 v65, 0xffff0000, v4
	v_cvt_pk_bf16_f32 v39, v66, v67
	v_cvt_pk_bf16_f32 v36, v36, v37
	ds_write_b16 v190, v64
	ds_write_b16_d16_hi v190, v64 offset:272
	ds_write_b16 v190, v38 offset:544
	ds_write_b16_d16_hi v190, v38 offset:816
	ds_write_b16 v190, v39 offset:1088
	ds_write_b16_d16_hi v190, v39 offset:1360
	ds_write_b16 v190, v36 offset:1632
	ds_write_b16_d16_hi v190, v36 offset:1904
	ds_read_b64 v[36:37], v191
	v_lshlrev_b32_e32 v64, 16, v4
	v_lshlrev_b32_e32 v38, 16, v5
	v_and_b32_e32 v39, 0xffff0000, v5
	v_lshlrev_b32_e32 v68, 16, v6
	v_and_b32_e32 v69, 0xffff0000, v6
	v_lshlrev_b32_e32 v66, 16, v7
	v_and_b32_e32 v67, 0xffff0000, v7
	s_waitcnt lgkmcnt(0)
	v_sub_f32_e32 v39, v39, v36
	v_sub_f32_e32 v38, v38, v36
	v_sub_f32_e32 v65, v65, v36
	v_sub_f32_e32 v64, v64, v36
	v_sub_f32_e32 v67, v67, v36
	v_sub_f32_e32 v66, v66, v36
	v_sub_f32_e32 v69, v69, v36
	v_sub_f32_e32 v68, v68, v36
	v_pk_mul_f32 v[64:65], v[36:37], v[64:65] op_sel:[1,0]
	v_pk_mul_f32 v[38:39], v[36:37], v[38:39] op_sel:[1,0]
	v_pk_mul_f32 v[68:69], v[36:37], v[68:69] op_sel:[1,0]
	v_pk_mul_f32 v[36:37], v[36:37], v[66:67] op_sel:[1,0]
	v_pk_fma_f32 v[64:65], v[96:97], v[64:65], v[100:101]
	v_pk_fma_f32 v[34:35], v[34:35], v[36:37], v[94:95]
	v_pk_fma_f32 v[32:33], v[32:33], v[68:69], v[92:93]
	v_cvt_pk_bf16_f32 v36, v64, v65
	v_pk_fma_f32 v[38:39], v[98:99], v[38:39], v[102:103]
	s_nop 0
	v_cvt_pk_bf16_f32 v37, v38, v39
	v_cvt_pk_bf16_f32 v32, v32, v33
	v_cvt_pk_bf16_f32 v33, v34, v35
	ds_write_b16 v192, v36
	ds_write_b16_d16_hi v192, v36 offset:272
	ds_write_b16 v192, v37 offset:544
	ds_write_b16_d16_hi v192, v37 offset:816
	ds_write_b16 v192, v32 offset:1088
	ds_write_b16_d16_hi v192, v32 offset:1360
	ds_write_b16 v192, v33 offset:1632
	ds_write_b16_d16_hi v192, v33 offset:1904

.LBB0_759:
	s_nop 0
	ds_read_b128 v[96:99], v248 offset:3600
	ds_read_b128 v[104:107], v248 offset:3584
	ds_read_b128 v[100:103], v248 offset:7696
	ds_read_b128 v[108:111], v248 offset:7680
	v_add_co_u32_e32 v32, vcc, 0x38000, v148
	s_waitcnt vmcnt(5)
	v_mov_b64_e32 v[36:37], v[80:81]
	v_addc_co_u32_e32 v33, vcc, 0, v149, vcc
	global_load_dwordx4 v[92:95], v[32:33], off
	global_load_dwordx4 v[84:87], v[32:33], off offset:64
	s_and_b64 vcc, exec, s[4:5]
	v_mov_b64_e32 v[38:39], v[82:83]
	s_cbranch_vccnz .LBB0_761
	v_add_co_u32_e32 v32, vcc, 0x38000, v148
	s_nop 1
	v_addc_co_u32_e32 v33, vcc, 0, v149, vcc
	global_load_dwordx4 v[36:39], v[32:33], off offset:128

; #define LAS __attribute__((address_space(3)))
; __device__ __forceinline__ unsigned cvt_pk_bf16(float lo, float hi) { unsigned r; asm volatile("v_cvt_pk_bf16_f32 %0, %1, %2" : "=v"(r) : "v"(lo), "v"(hi)); return r; }
; __device__ __forceinline__ float bf_lo(unsigned u) { return __uint_as_float(u << 16); }
; __device__ __forceinline__ float bf_hi(unsigned u) { return __uint_as_float(u & 0xffff0000u); }
; __global__ void __launch_bounds__(NTHR, 2) fwd_megakernel(Args args) {
;     ...
;                 for (int k = 0; k < 4; ++k) if (k < nk) { const int j = jb + 32 * k; const u32x4 v = pv[k]; const f32x2 ms = st[j];
;                     const f32x4 x0 = (f32x4){bf_lo(v.x), bf_hi(v.x), bf_lo(v.y), bf_hi(v.y)}, x1 = (f32x4){bf_lo(v.z), bf_hi(v.z), bf_lo(v.w), bf_hi(v.w)};
;                     const f32x4 y0 = (x0 - ms.x) * ms.y * pg0 + pb0, y1 = (x1 - ms.x) * ms.y * pg1 + pb1;
;                     LAS bf16_t* d = Bc + (c8 * 8) * LDB + (j ^ (8 * c8));
;                     const unsigned p0 = cvt_pk_bf16(y0[0], y0[1]), p1 = cvt_pk_bf16(y0[2], y0[3]), p2 = cvt_pk_bf16(y1[0], y1[1]), p3 = cvt_pk_bf16(y1[2], y1[3]);
;                     d[0 * LDB] = (bf16_t)(p0 & 0xffffu); d[1 * LDB] = (bf16_t)(p0 >> 16); d[2 * LDB] = (bf16_t)(p1 & 0xffffu); d[3 * LDB] = (bf16_t)(p1 >> 16);
;                     d[4 * LDB] = (bf16_t)(p2 & 0xffffu); d[5 * LDB] = (bf16_t)(p2 >> 16); d[6 * LDB] = (bf16_t)(p3 & 0xffffu); d[7 * LDB] = (bf16_t)(p3 >> 16); }
.LBB0_767:
	ds_read_b64 v[72:73], v181
	s_waitcnt vmcnt(6)
	v_lshlrev_b32_e32 v76, 16, v116
	v_and_b32_e32 v77, 0xffff0000, v116
	v_lshlrev_b32_e32 v74, 16, v117
	v_and_b32_e32 v75, 0xffff0000, v117
	v_lshlrev_b32_e32 v80, 16, v118
	v_and_b32_e32 v81, 0xffff0000, v118
	v_lshlrev_b32_e32 v78, 16, v119
	v_and_b32_e32 v79, 0xffff0000, v119
	s_waitcnt lgkmcnt(0)
	v_sub_f32_e32 v77, v77, v72
	v_sub_f32_e32 v76, v76, v72
	v_sub_f32_e32 v75, v75, v72
	v_sub_f32_e32 v74, v74, v72
	v_pk_mul_f32 v[76:77], v[72:73], v[76:77] op_sel:[1,0]
	v_sub_f32_e32 v79, v79, v72
	v_sub_f32_e32 v78, v78, v72
	v_sub_f32_e32 v81, v81, v72
	v_sub_f32_e32 v80, v80, v72
	v_pk_mul_f32 v[74:75], v[72:73], v[74:75] op_sel:[1,0]
	s_waitcnt vmcnt(5)
	v_pk_fma_f32 v[76:77], v[104:105], v[76:77], v[108:109]
	v_pk_mul_f32 v[80:81], v[72:73], v[80:81] op_sel:[1,0]
	v_pk_mul_f32 v[72:73], v[72:73], v[78:79] op_sel:[1,0]
	v_pk_fma_f32 v[74:75], v[106:107], v[74:75], v[110:111]
	v_pk_fma_f32 v[72:73], v[98:99], v[72:73], v[102:103]
	v_cvt_pk_bf16_f32 v76, v76, v77
	v_pk_fma_f32 v[78:79], v[96:97], v[80:81], v[100:101]
	v_cvt_pk_bf16_f32 v74, v74, v75
	v_and_b32_e32 v77, 0xffff0000, v112
	v_cvt_pk_bf16_f32 v75, v78, v79
	v_cvt_pk_bf16_f32 v72, v72, v73
	ds_write_b16 v186, v76 offset:34816
	ds_write_b16_d16_hi v186, v76 offset:35088
	ds_write_b16 v186, v74 offset:35360
	ds_write_b16_d16_hi v186, v74 offset:35632
	ds_write_b16 v186, v75 offset:35904
	ds_write_b16_d16_hi v186, v75 offset:36176
	ds_write_b16 v186, v72 offset:36448
	ds_write_b16_d16_hi v186, v72 offset:36720
	ds_read_b64 v[72:73], v187
	v_lshlrev_b32_e32 v76, 16, v112
	v_lshlrev_b32_e32 v74, 16, v113
	v_and_b32_e32 v75, 0xffff0000, v113
	v_lshlrev_b32_e32 v80, 16, v114
	v_and_b32_e32 v81, 0xffff0000, v114
	v_lshlrev_b32_e32 v78, 16, v115
	v_and_b32_e32 v79, 0xffff0000, v115
	s_waitcnt lgkmcnt(0)
	v_sub_f32_e32 v77, v77, v72
	v_sub_f32_e32 v76, v76, v72
	v_sub_f32_e32 v75, v75, v72
	v_sub_f32_e32 v74, v74, v72
	v_pk_mul_f32 v[76:77], v[72:73], v[76:77] op_sel:[1,0]
	v_sub_f32_e32 v79, v79, v72
	v_sub_f32_e32 v78, v78, v72
	v_sub_f32_e32 v81, v81, v72
	v_sub_f32_e32 v80, v80, v72
	v_pk_mul_f32 v[74:75], v[72:73], v[74:75] op_sel:[1,0]
	v_pk_fma_f32 v[76:77], v[104:105], v[76:77], v[108:109]
	v_pk_mul_f32 v[80:81], v[72:73], v[80:81] op_sel:[1,0]
	v_pk_mul_f32 v[72:73], v[72:73], v[78:79] op_sel:[1,0]
	v_pk_fma_f32 v[74:75], v[106:107], v[74:75], v[110:111]
	v_pk_fma_f32 v[72:73], v[98:99], v[72:73], v[102:103]
	v_cvt_pk_bf16_f32 v76, v76, v77
	s_and_b64 vcc, exec, s[4:5]
	v_pk_fma_f32 v[78:79], v[96:97], v[80:81], v[100:101]
	v_cvt_pk_bf16_f32 v74, v74, v75
	s_nop 0
	v_cvt_pk_bf16_f32 v75, v78, v79
	v_cvt_pk_bf16_f32 v72, v72, v73
	ds_write_b16 v188, v76 offset:34816
	ds_write_b16_d16_hi v188, v76 offset:35088
	ds_write_b16 v188, v74 offset:35360
	ds_write_b16_d16_hi v188, v74 offset:35632
	ds_write_b16 v188, v75 offset:35904
	ds_write_b16_d16_hi v188, v75 offset:36176
	ds_write_b16 v188, v72 offset:36448
	ds_write_b16_d16_hi v188, v72 offset:36720
	s_cbranch_vccnz .LBB0_769
	ds_read_b64 v[72:73], v189
	v_lshlrev_b32_e32 v76, 16, v0
	v_and_b32_e32 v77, 0xffff0000, v0
	v_lshlrev_b32_e32 v74, 16, v1
	v_and_b32_e32 v75, 0xffff0000, v1
	v_lshlrev_b32_e32 v80, 16, v2
	v_and_b32_e32 v81, 0xffff0000, v2
	v_lshlrev_b32_e32 v78, 16, v3
	v_and_b32_e32 v79, 0xffff0000, v3
	s_waitcnt lgkmcnt(0)
	v_sub_f32_e32 v77, v77, v72
	v_sub_f32_e32 v76, v76, v72
	v_sub_f32_e32 v75, v75, v72
	v_sub_f32_e32 v74, v74, v72
	v_pk_mul_f32 v[76:77], v[72:73], v[76:77] op_sel:[1,0]
	v_sub_f32_e32 v79, v79, v72
	v_sub_f32_e32 v78, v78, v72
	v_sub_f32_e32 v81, v81, v72
	v_sub_f32_e32 v80, v80, v72
	v_pk_mul_f32 v[74:75], v[72:73], v[74:75] op_sel:[1,0]
	v_pk_fma_f32 v[76:77], v[104:105], v[76:77], v[108:109]
	v_pk_mul_f32 v[80:81], v[72:73], v[80:81] op_sel:[1,0]
	v_pk_mul_f32 v[72:73], v[72:73], v[78:79] op_sel:[1,0]
	v_pk_fma_f32 v[74:75], v[106:107], v[74:75], v[110:111]
	v_pk_fma_f32 v[72:73], v[98:99], v[72:73], v[102:103]
	v_cvt_pk_bf16_f32 v76, v76, v77
	v_pk_fma_f32 v[78:79], v[96:97], v[80:81], v[100:101]
	v_cvt_pk_bf16_f32 v74, v74, v75
	v_and_b32_e32 v77, 0xffff0000, v4
	v_cvt_pk_bf16_f32 v75, v78, v79
	v_cvt_pk_bf16_f32 v72, v72, v73
	ds_write_b16 v190, v76 offset:34816
	ds_write_b16_d16_hi v190, v76 offset:35088
	ds_write_b16 v190, v74 offset:35360
	ds_write_b16_d16_hi v190, v74 offset:35632
	ds_write_b16 v190, v75 offset:35904
	ds_write_b16_d16_hi v190, v75 offset:36176
	ds_write_b16 v190, v72 offset:36448
	ds_write_b16_d16_hi v190, v72 offset:36720
	ds_read_b64 v[72:73], v191
	v_lshlrev_b32_e32 v76, 16, v4
	v_lshlrev_b32_e32 v74, 16, v5
	v_and_b32_e32 v75, 0xffff0000, v5
	v_lshlrev_b32_e32 v80, 16, v6
	v_and_b32_e32 v81, 0xffff0000, v6
	v_lshlrev_b32_e32 v78, 16, v7
	v_and_b32_e32 v79, 0xffff0000, v7
	s_waitcnt lgkmcnt(0)
	v_sub_f32_e32 v77, v77, v72
	v_sub_f32_e32 v76, v76, v72
	v_sub_f32_e32 v75, v75, v72
	v_sub_f32_e32 v74, v74, v72
	v_pk_mul_f32 v[76:77], v[72:73], v[76:77] op_sel:[1,0]
	v_sub_f32_e32 v79, v79, v72
	v_sub_f32_e32 v78, v78, v72
	v_sub_f32_e32 v81, v81, v72
	v_sub_f32_e32 v80, v80, v72
	v_pk_mul_f32 v[74:75], v[72:73], v[74:75] op_sel:[1,0]
	v_pk_fma_f32 v[76:77], v[104:105], v[76:77], v[108:109]
	v_pk_mul_f32 v[80:81], v[72:73], v[80:81] op_sel:[1,0]
	v_pk_mul_f32 v[72:73], v[72:73], v[78:79] op_sel:[1,0]
	v_pk_fma_f32 v[74:75], v[106:107], v[74:75], v[110:111]
	v_pk_fma_f32 v[72:73], v[98:99], v[72:73], v[102:103]
	v_cvt_pk_bf16_f32 v76, v76, v77
	v_pk_fma_f32 v[78:79], v[96:97], v[80:81], v[100:101]
	v_cvt_pk_bf16_f32 v74, v74, v75
	s_nop 0
	v_cvt_pk_bf16_f32 v75, v78, v79
	v_cvt_pk_bf16_f32 v72, v72, v73
	ds_write_b16 v192, v76 offset:34816
	ds_write_b16_d16_hi v192, v76 offset:35088
	ds_write_b16 v192, v74 offset:35360
	ds_write_b16_d16_hi v192, v74 offset:35632
	ds_write_b16 v192, v75 offset:35904
	ds_write_b16_d16_hi v192, v75 offset:36176
	ds_write_b16 v192, v72 offset:36448
	ds_write_b16_d16_hi v192, v72 offset:36720
